# GEMM1 epilogue rotary blocks rewritten branch-free (8 partner exchanges + one wait per block) on top of previous best
# speedup vs baseline: 1.1643x; 1.0133x over previous
.LBB0_123:
	s_add_i32 s28, s27, 0xfffff980
	s_cmpk_lt_u32 s28, 0x400
	s_cselect_b64 s[28:29], -1, 0
	s_and_b64 s[28:29], s[44:45], s[28:29]
	v_cndmask_b32_e64 v128, 0, 1, s[28:29]
	v_cmp_ne_u32_e64 s[38:39], 1, v128
	s_andn2_b64 vcc, exec, s[28:29]
	s_cbranch_vccnz .LBB0_173
	v_mov_b32_e32 v182, v181
	v_xor_b32_e32 v183, 16, v180
	v_and_b32_e32 v182, 0xfff, v182
	v_lshlrev_b32_e32 v183, 2, v183
	v_cvt_f32_u32_e32 v182, v182
	v_cmp_eq_u32_e64 s[60:61], 0, v171
	v_cmp_gt_u32_e64 s[68:69], 2, v171
	ds_bpermute_b32 v184, v183, v120
	ds_bpermute_b32 v185, v183, v121
	ds_bpermute_b32 v186, v183, v122
	ds_bpermute_b32 v187, v183, v123
	ds_bpermute_b32 v188, v183, v124
	ds_bpermute_b32 v189, v183, v125
	ds_bpermute_b32 v190, v183, v126
	ds_bpermute_b32 v191, v183, v127
	v_mov_b32_e32 v192, 1.0
	v_cndmask_b32_e64 v192, v192, -1.0, s[60:61]
	v_mul_f32_e32 v194, 0.15915494, v182
	v_rndne_f32_e32 v194, v194
	v_fma_f32 v194, v182, 0.15915494, -v194
	v_mul_f32_e32 v194, 0x40c90fdb, v194
	v_mul_f32_e32 v194, 0.15915494, v194
	v_sin_f32_e32 v204, v194
	v_cos_f32_e32 v196, v194
	v_mul_f32_e32 v193, 0x3e4693af, v182
	v_mul_f32_e32 v194, 0.15915494, v193
	v_rndne_f32_e32 v194, v194
	v_fma_f32 v194, v193, 0.15915494, -v194
	v_mul_f32_e32 v194, 0x40c90fdb, v194
	v_mul_f32_e32 v194, 0.15915494, v194
	v_sin_f32_e32 v205, v194
	v_cos_f32_e32 v197, v194
	v_mul_f32_e32 v193, 0x3d1a08c8, v182
	v_mul_f32_e32 v194, 0.15915494, v193
	v_rndne_f32_e32 v194, v194
	v_fma_f32 v194, v193, 0.15915494, -v194
	v_mul_f32_e32 v194, 0x40c90fdb, v194
	v_mul_f32_e32 v194, 0.15915494, v194
	v_sin_f32_e32 v206, v194
	v_cos_f32_e32 v198, v194
	v_mul_f32_e32 v193, 0x3beef74e, v182
	v_mul_f32_e32 v194, 0.15915494, v193
	v_rndne_f32_e32 v194, v194
	v_fma_f32 v194, v193, 0.15915494, -v194
	v_mul_f32_e32 v194, 0x40c90fdb, v194
	v_mul_f32_e32 v194, 0.15915494, v194
	v_sin_f32_e32 v207, v194
	v_cos_f32_e32 v199, v194
	v_mul_f32_e32 v193, 0x3ab95d22, v182
	v_mul_f32_e32 v194, 0.15915494, v193
	v_rndne_f32_e32 v194, v194
	v_fma_f32 v194, v193, 0.15915494, -v194
	v_mul_f32_e32 v194, 0x40c90fdb, v194
	v_mul_f32_e32 v194, 0.15915494, v194
	v_sin_f32_e32 v208, v194
	v_cos_f32_e32 v200, v194
	v_mul_f32_e32 v193, 0x398fc8f8, v182
	v_mul_f32_e32 v194, 0.15915494, v193
	v_rndne_f32_e32 v194, v194
	v_fma_f32 v194, v193, 0.15915494, -v194
	v_mul_f32_e32 v194, 0x40c90fdb, v194
	v_mul_f32_e32 v194, 0.15915494, v194
	v_sin_f32_e32 v209, v194
	v_cos_f32_e32 v201, v194
	v_mul_f32_e32 v193, 0x385f10c4, v182
	v_mul_f32_e32 v194, 0.15915494, v193
	v_rndne_f32_e32 v194, v194
	v_fma_f32 v194, v193, 0.15915494, -v194
	v_mul_f32_e32 v194, 0x40c90fdb, v194
	v_mul_f32_e32 v194, 0.15915494, v194
	v_sin_f32_e32 v210, v194
	v_cos_f32_e32 v202, v194
	v_mul_f32_e32 v193, 0x372d07a7, v182
	v_mul_f32_e32 v194, 0.15915494, v193
	v_rndne_f32_e32 v194, v194
	v_fma_f32 v194, v193, 0.15915494, -v194
	v_mul_f32_e32 v194, 0x40c90fdb, v194
	v_mul_f32_e32 v194, 0.15915494, v194
	v_sin_f32_e32 v211, v194
	v_cos_f32_e32 v203, v194
	s_waitcnt lgkmcnt(0)
	v_mul_f32_e32 v204, v204, v184
	v_mul_f32_e32 v196, v196, v120
	v_mul_f32_e32 v204, v204, v192
	v_add_f32_e32 v196, v196, v204
	v_cndmask_b32_e64 v128, v120, v196, s[68:69]
	v_mul_f32_e32 v205, v205, v185
	v_mul_f32_e32 v197, v197, v121
	v_mul_f32_e32 v205, v205, v192
	v_add_f32_e32 v197, v197, v205
	v_cndmask_b32_e64 v129, v121, v197, s[68:69]
	v_mul_f32_e32 v206, v206, v186
	v_mul_f32_e32 v198, v198, v122
	v_mul_f32_e32 v206, v206, v192
	v_add_f32_e32 v198, v198, v206
	v_cndmask_b32_e64 v130, v122, v198, s[68:69]
	v_mul_f32_e32 v207, v207, v187
	v_mul_f32_e32 v199, v199, v123
	v_mul_f32_e32 v207, v207, v192
	v_add_f32_e32 v199, v199, v207
	v_cndmask_b32_e64 v131, v123, v199, s[68:69]
	v_mul_f32_e32 v208, v208, v188
	v_mul_f32_e32 v200, v200, v124
	v_mul_f32_e32 v208, v208, v192
	v_add_f32_e32 v200, v200, v208
	v_cndmask_b32_e64 v132, v124, v200, s[68:69]
	v_mul_f32_e32 v209, v209, v189
	v_mul_f32_e32 v201, v201, v125
	v_mul_f32_e32 v209, v209, v192
	v_add_f32_e32 v201, v201, v209
	v_cndmask_b32_e64 v133, v125, v201, s[68:69]
	v_mul_f32_e32 v210, v210, v190
	v_mul_f32_e32 v202, v202, v126
	v_mul_f32_e32 v210, v210, v192
	v_add_f32_e32 v202, v202, v210
	v_cndmask_b32_e64 v134, v126, v202, s[68:69]
	v_mul_f32_e32 v211, v211, v191
	v_mul_f32_e32 v203, v203, v127
	v_mul_f32_e32 v211, v211, v192
	v_add_f32_e32 v203, v203, v211
	v_cndmask_b32_e64 v135, v127, v203, s[68:69]
	s_branch .LBB0_174

.LBB0_174:
	v_or_b32_e32 v160, s54, v150
	v_mov_b64_e32 v[124:125], s[78:79]
	v_ashrrev_i32_e32 v161, 31, v160
	v_mad_i64_i32 v[124:125], s[28:29], v181, s26, v[124:125]
	v_cvt_pk_bf16_f32 v120, v128, v129
	v_cvt_pk_bf16_f32 v121, v130, v131
	v_cvt_pk_bf16_f32 v122, v132, v133
	v_cvt_pk_bf16_f32 v123, v134, v135
	v_lshl_add_u64 v[124:125], v[160:161], 1, v[124:125]
	s_and_b64 vcc, exec, s[38:39]
	v_or_b32_e32 v128, 16, v181
	global_store_dwordx4 v[124:125], v[120:123], off nt
	s_cbranch_vccnz .LBB0_224
	v_add_u32_e32 v182, 16, v181
	v_xor_b32_e32 v183, 16, v180
	v_and_b32_e32 v182, 0xfff, v182
	v_lshlrev_b32_e32 v183, 2, v183
	v_cvt_f32_u32_e32 v182, v182
	v_cmp_eq_u32_e64 s[60:61], 0, v171
	v_cmp_gt_u32_e64 s[68:69], 2, v171
	ds_bpermute_b32 v184, v183, v112
	ds_bpermute_b32 v185, v183, v113
	ds_bpermute_b32 v186, v183, v114
	ds_bpermute_b32 v187, v183, v115
	ds_bpermute_b32 v188, v183, v116
	ds_bpermute_b32 v189, v183, v117
	ds_bpermute_b32 v190, v183, v118
	ds_bpermute_b32 v191, v183, v119
	v_mov_b32_e32 v192, 1.0
	v_cndmask_b32_e64 v192, v192, -1.0, s[60:61]
	v_mul_f32_e32 v194, 0.15915494, v182
	v_rndne_f32_e32 v194, v194
	v_fma_f32 v194, v182, 0.15915494, -v194
	v_mul_f32_e32 v194, 0x40c90fdb, v194
	v_mul_f32_e32 v194, 0.15915494, v194
	v_sin_f32_e32 v204, v194
	v_cos_f32_e32 v196, v194
	v_mul_f32_e32 v193, 0x3e4693af, v182
	v_mul_f32_e32 v194, 0.15915494, v193
	v_rndne_f32_e32 v194, v194
	v_fma_f32 v194, v193, 0.15915494, -v194
	v_mul_f32_e32 v194, 0x40c90fdb, v194
	v_mul_f32_e32 v194, 0.15915494, v194
	v_sin_f32_e32 v205, v194
	v_cos_f32_e32 v197, v194
	v_mul_f32_e32 v193, 0x3d1a08c8, v182
	v_mul_f32_e32 v194, 0.15915494, v193
	v_rndne_f32_e32 v194, v194
	v_fma_f32 v194, v193, 0.15915494, -v194
	v_mul_f32_e32 v194, 0x40c90fdb, v194
	v_mul_f32_e32 v194, 0.15915494, v194
	v_sin_f32_e32 v206, v194
	v_cos_f32_e32 v198, v194
	v_mul_f32_e32 v193, 0x3beef74e, v182
	v_mul_f32_e32 v194, 0.15915494, v193
	v_rndne_f32_e32 v194, v194
	v_fma_f32 v194, v193, 0.15915494, -v194
	v_mul_f32_e32 v194, 0x40c90fdb, v194
	v_mul_f32_e32 v194, 0.15915494, v194
	v_sin_f32_e32 v207, v194
	v_cos_f32_e32 v199, v194
	v_mul_f32_e32 v193, 0x3ab95d22, v182
	v_mul_f32_e32 v194, 0.15915494, v193
	v_rndne_f32_e32 v194, v194
	v_fma_f32 v194, v193, 0.15915494, -v194
	v_mul_f32_e32 v194, 0x40c90fdb, v194
	v_mul_f32_e32 v194, 0.15915494, v194
	v_sin_f32_e32 v208, v194
	v_cos_f32_e32 v200, v194
	v_mul_f32_e32 v193, 0x398fc8f8, v182
	v_mul_f32_e32 v194, 0.15915494, v193
	v_rndne_f32_e32 v194, v194
	v_fma_f32 v194, v193, 0.15915494, -v194
	v_mul_f32_e32 v194, 0x40c90fdb, v194
	v_mul_f32_e32 v194, 0.15915494, v194
	v_sin_f32_e32 v209, v194
	v_cos_f32_e32 v201, v194
	v_mul_f32_e32 v193, 0x385f10c4, v182
	v_mul_f32_e32 v194, 0.15915494, v193
	v_rndne_f32_e32 v194, v194
	v_fma_f32 v194, v193, 0.15915494, -v194
	v_mul_f32_e32 v194, 0x40c90fdb, v194
	v_mul_f32_e32 v194, 0.15915494, v194
	v_sin_f32_e32 v210, v194
	v_cos_f32_e32 v202, v194
	v_mul_f32_e32 v193, 0x372d07a7, v182
	v_mul_f32_e32 v194, 0.15915494, v193
	v_rndne_f32_e32 v194, v194
	v_fma_f32 v194, v193, 0.15915494, -v194
	v_mul_f32_e32 v194, 0x40c90fdb, v194
	v_mul_f32_e32 v194, 0.15915494, v194
	v_sin_f32_e32 v211, v194
	v_cos_f32_e32 v203, v194
	s_waitcnt lgkmcnt(0)
	v_mul_f32_e32 v204, v204, v184
	v_mul_f32_e32 v196, v196, v112
	v_mul_f32_e32 v204, v204, v192
	v_add_f32_e32 v196, v196, v204
	v_cndmask_b32_e64 v120, v112, v196, s[68:69]
	v_mul_f32_e32 v205, v205, v185
	v_mul_f32_e32 v197, v197, v113
	v_mul_f32_e32 v205, v205, v192
	v_add_f32_e32 v197, v197, v205
	v_cndmask_b32_e64 v121, v113, v197, s[68:69]
	v_mul_f32_e32 v206, v206, v186
	v_mul_f32_e32 v198, v198, v114
	v_mul_f32_e32 v206, v206, v192
	v_add_f32_e32 v198, v198, v206
	v_cndmask_b32_e64 v122, v114, v198, s[68:69]
	v_mul_f32_e32 v207, v207, v187
	v_mul_f32_e32 v199, v199, v115
	v_mul_f32_e32 v207, v207, v192
	v_add_f32_e32 v199, v199, v207
	v_cndmask_b32_e64 v123, v115, v199, s[68:69]
	v_mul_f32_e32 v208, v208, v188
	v_mul_f32_e32 v200, v200, v116
	v_mul_f32_e32 v208, v208, v192
	v_add_f32_e32 v200, v200, v208
	v_cndmask_b32_e64 v124, v116, v200, s[68:69]
	v_mul_f32_e32 v209, v209, v189
	v_mul_f32_e32 v201, v201, v117
	v_mul_f32_e32 v209, v209, v192
	v_add_f32_e32 v201, v201, v209
	v_cndmask_b32_e64 v125, v117, v201, s[68:69]
	v_mul_f32_e32 v210, v210, v190
	v_mul_f32_e32 v202, v202, v118
	v_mul_f32_e32 v210, v210, v192
	v_add_f32_e32 v202, v202, v210
	v_cndmask_b32_e64 v126, v118, v202, s[68:69]
	v_mul_f32_e32 v211, v211, v191
	v_mul_f32_e32 v203, v203, v119
	v_mul_f32_e32 v211, v211, v192
	v_add_f32_e32 v203, v203, v211
	v_cndmask_b32_e64 v127, v119, v203, s[68:69]
	s_branch .LBB0_225

.LBB0_225:
	v_mov_b64_e32 v[116:117], s[78:79]
	v_mad_i64_i32 v[116:117], s[28:29], v128, s26, v[116:117]
	v_cvt_pk_bf16_f32 v112, v120, v121
	v_cvt_pk_bf16_f32 v113, v122, v123
	v_cvt_pk_bf16_f32 v114, v124, v125
	v_cvt_pk_bf16_f32 v115, v126, v127
	v_lshl_add_u64 v[116:117], v[160:161], 1, v[116:117]
	s_and_b64 vcc, exec, s[38:39]
	v_or_b32_e32 v120, 32, v181
	global_store_dwordx4 v[116:117], v[112:115], off nt
	s_cbranch_vccnz .LBB0_275
	v_add_u32_e32 v182, 32, v181
	v_xor_b32_e32 v183, 16, v180
	v_and_b32_e32 v182, 0xfff, v182
	v_lshlrev_b32_e32 v183, 2, v183
	v_cvt_f32_u32_e32 v182, v182
	v_cmp_eq_u32_e64 s[60:61], 0, v171
	v_cmp_gt_u32_e64 s[68:69], 2, v171
	ds_bpermute_b32 v184, v183, v104
	ds_bpermute_b32 v185, v183, v105
	ds_bpermute_b32 v186, v183, v106
	ds_bpermute_b32 v187, v183, v107
	ds_bpermute_b32 v188, v183, v108
	ds_bpermute_b32 v189, v183, v109
	ds_bpermute_b32 v190, v183, v110
	ds_bpermute_b32 v191, v183, v111
	v_mov_b32_e32 v192, 1.0
	v_cndmask_b32_e64 v192, v192, -1.0, s[60:61]
	v_mul_f32_e32 v194, 0.15915494, v182
	v_rndne_f32_e32 v194, v194
	v_fma_f32 v194, v182, 0.15915494, -v194
	v_mul_f32_e32 v194, 0x40c90fdb, v194
	v_mul_f32_e32 v194, 0.15915494, v194
	v_sin_f32_e32 v204, v194
	v_cos_f32_e32 v196, v194
	v_mul_f32_e32 v193, 0x3e4693af, v182
	v_mul_f32_e32 v194, 0.15915494, v193
	v_rndne_f32_e32 v194, v194
	v_fma_f32 v194, v193, 0.15915494, -v194
	v_mul_f32_e32 v194, 0x40c90fdb, v194
	v_mul_f32_e32 v194, 0.15915494, v194
	v_sin_f32_e32 v205, v194
	v_cos_f32_e32 v197, v194
	v_mul_f32_e32 v193, 0x3d1a08c8, v182
	v_mul_f32_e32 v194, 0.15915494, v193
	v_rndne_f32_e32 v194, v194
	v_fma_f32 v194, v193, 0.15915494, -v194
	v_mul_f32_e32 v194, 0x40c90fdb, v194
	v_mul_f32_e32 v194, 0.15915494, v194
	v_sin_f32_e32 v206, v194
	v_cos_f32_e32 v198, v194
	v_mul_f32_e32 v193, 0x3beef74e, v182
	v_mul_f32_e32 v194, 0.15915494, v193
	v_rndne_f32_e32 v194, v194
	v_fma_f32 v194, v193, 0.15915494, -v194
	v_mul_f32_e32 v194, 0x40c90fdb, v194
	v_mul_f32_e32 v194, 0.15915494, v194
	v_sin_f32_e32 v207, v194
	v_cos_f32_e32 v199, v194
	v_mul_f32_e32 v193, 0x3ab95d22, v182
	v_mul_f32_e32 v194, 0.15915494, v193
	v_rndne_f32_e32 v194, v194
	v_fma_f32 v194, v193, 0.15915494, -v194
	v_mul_f32_e32 v194, 0x40c90fdb, v194
	v_mul_f32_e32 v194, 0.15915494, v194
	v_sin_f32_e32 v208, v194
	v_cos_f32_e32 v200, v194
	v_mul_f32_e32 v193, 0x398fc8f8, v182
	v_mul_f32_e32 v194, 0.15915494, v193
	v_rndne_f32_e32 v194, v194
	v_fma_f32 v194, v193, 0.15915494, -v194
	v_mul_f32_e32 v194, 0x40c90fdb, v194
	v_mul_f32_e32 v194, 0.15915494, v194
	v_sin_f32_e32 v209, v194
	v_cos_f32_e32 v201, v194
	v_mul_f32_e32 v193, 0x385f10c4, v182
	v_mul_f32_e32 v194, 0.15915494, v193
	v_rndne_f32_e32 v194, v194
	v_fma_f32 v194, v193, 0.15915494, -v194
	v_mul_f32_e32 v194, 0x40c90fdb, v194
	v_mul_f32_e32 v194, 0.15915494, v194
	v_sin_f32_e32 v210, v194
	v_cos_f32_e32 v202, v194
	v_mul_f32_e32 v193, 0x372d07a7, v182
	v_mul_f32_e32 v194, 0.15915494, v193
	v_rndne_f32_e32 v194, v194
	v_fma_f32 v194, v193, 0.15915494, -v194
	v_mul_f32_e32 v194, 0x40c90fdb, v194
	v_mul_f32_e32 v194, 0.15915494, v194
	v_sin_f32_e32 v211, v194
	v_cos_f32_e32 v203, v194
	s_waitcnt lgkmcnt(0)
	v_mul_f32_e32 v204, v204, v184
	v_mul_f32_e32 v196, v196, v104
	v_mul_f32_e32 v204, v204, v192
	v_add_f32_e32 v196, v196, v204
	v_cndmask_b32_e64 v112, v104, v196, s[68:69]
	v_mul_f32_e32 v205, v205, v185
	v_mul_f32_e32 v197, v197, v105
	v_mul_f32_e32 v205, v205, v192
	v_add_f32_e32 v197, v197, v205
	v_cndmask_b32_e64 v113, v105, v197, s[68:69]
	v_mul_f32_e32 v206, v206, v186
	v_mul_f32_e32 v198, v198, v106
	v_mul_f32_e32 v206, v206, v192
	v_add_f32_e32 v198, v198, v206
	v_cndmask_b32_e64 v114, v106, v198, s[68:69]
	v_mul_f32_e32 v207, v207, v187
	v_mul_f32_e32 v199, v199, v107
	v_mul_f32_e32 v207, v207, v192
	v_add_f32_e32 v199, v199, v207
	v_cndmask_b32_e64 v115, v107, v199, s[68:69]
	v_mul_f32_e32 v208, v208, v188
	v_mul_f32_e32 v200, v200, v108
	v_mul_f32_e32 v208, v208, v192
	v_add_f32_e32 v200, v200, v208
	v_cndmask_b32_e64 v116, v108, v200, s[68:69]
	v_mul_f32_e32 v209, v209, v189
	v_mul_f32_e32 v201, v201, v109
	v_mul_f32_e32 v209, v209, v192
	v_add_f32_e32 v201, v201, v209
	v_cndmask_b32_e64 v117, v109, v201, s[68:69]
	v_mul_f32_e32 v210, v210, v190
	v_mul_f32_e32 v202, v202, v110
	v_mul_f32_e32 v210, v210, v192
	v_add_f32_e32 v202, v202, v210
	v_cndmask_b32_e64 v118, v110, v202, s[68:69]
	v_mul_f32_e32 v211, v211, v191
	v_mul_f32_e32 v203, v203, v111
	v_mul_f32_e32 v211, v211, v192
	v_add_f32_e32 v203, v203, v211
	v_cndmask_b32_e64 v119, v111, v203, s[68:69]
	s_branch .LBB0_276

.LBB0_276:
	v_mov_b64_e32 v[108:109], s[78:79]
	v_mad_i64_i32 v[108:109], s[28:29], v120, s26, v[108:109]
	v_cvt_pk_bf16_f32 v104, v112, v113
	v_cvt_pk_bf16_f32 v105, v114, v115
	v_cvt_pk_bf16_f32 v106, v116, v117
	v_cvt_pk_bf16_f32 v107, v118, v119
	v_lshl_add_u64 v[108:109], v[160:161], 1, v[108:109]
	s_and_b64 vcc, exec, s[38:39]
	v_or_b32_e32 v112, 48, v181
	global_store_dwordx4 v[108:109], v[104:107], off nt
	s_cbranch_vccnz .LBB0_326
	v_add_u32_e32 v182, 48, v181
	v_xor_b32_e32 v183, 16, v180
	v_and_b32_e32 v182, 0xfff, v182
	v_lshlrev_b32_e32 v183, 2, v183
	v_cvt_f32_u32_e32 v182, v182
	v_cmp_eq_u32_e64 s[60:61], 0, v171
	v_cmp_gt_u32_e64 s[68:69], 2, v171
	ds_bpermute_b32 v184, v183, v96
	ds_bpermute_b32 v185, v183, v97
	ds_bpermute_b32 v186, v183, v98
	ds_bpermute_b32 v187, v183, v99
	ds_bpermute_b32 v188, v183, v100
	ds_bpermute_b32 v189, v183, v101
	ds_bpermute_b32 v190, v183, v102
	ds_bpermute_b32 v191, v183, v103
	v_mov_b32_e32 v192, 1.0
	v_cndmask_b32_e64 v192, v192, -1.0, s[60:61]
	v_mul_f32_e32 v194, 0.15915494, v182
	v_rndne_f32_e32 v194, v194
	v_fma_f32 v194, v182, 0.15915494, -v194
	v_mul_f32_e32 v194, 0x40c90fdb, v194
	v_mul_f32_e32 v194, 0.15915494, v194
	v_sin_f32_e32 v204, v194
	v_cos_f32_e32 v196, v194
	v_mul_f32_e32 v193, 0x3e4693af, v182
	v_mul_f32_e32 v194, 0.15915494, v193
	v_rndne_f32_e32 v194, v194
	v_fma_f32 v194, v193, 0.15915494, -v194
	v_mul_f32_e32 v194, 0x40c90fdb, v194
	v_mul_f32_e32 v194, 0.15915494, v194
	v_sin_f32_e32 v205, v194
	v_cos_f32_e32 v197, v194
	v_mul_f32_e32 v193, 0x3d1a08c8, v182
	v_mul_f32_e32 v194, 0.15915494, v193
	v_rndne_f32_e32 v194, v194
	v_fma_f32 v194, v193, 0.15915494, -v194
	v_mul_f32_e32 v194, 0x40c90fdb, v194
	v_mul_f32_e32 v194, 0.15915494, v194
	v_sin_f32_e32 v206, v194
	v_cos_f32_e32 v198, v194
	v_mul_f32_e32 v193, 0x3beef74e, v182
	v_mul_f32_e32 v194, 0.15915494, v193
	v_rndne_f32_e32 v194, v194
	v_fma_f32 v194, v193, 0.15915494, -v194
	v_mul_f32_e32 v194, 0x40c90fdb, v194
	v_mul_f32_e32 v194, 0.15915494, v194
	v_sin_f32_e32 v207, v194
	v_cos_f32_e32 v199, v194
	v_mul_f32_e32 v193, 0x3ab95d22, v182
	v_mul_f32_e32 v194, 0.15915494, v193
	v_rndne_f32_e32 v194, v194
	v_fma_f32 v194, v193, 0.15915494, -v194
	v_mul_f32_e32 v194, 0x40c90fdb, v194
	v_mul_f32_e32 v194, 0.15915494, v194
	v_sin_f32_e32 v208, v194
	v_cos_f32_e32 v200, v194
	v_mul_f32_e32 v193, 0x398fc8f8, v182
	v_mul_f32_e32 v194, 0.15915494, v193
	v_rndne_f32_e32 v194, v194
	v_fma_f32 v194, v193, 0.15915494, -v194
	v_mul_f32_e32 v194, 0x40c90fdb, v194
	v_mul_f32_e32 v194, 0.15915494, v194
	v_sin_f32_e32 v209, v194
	v_cos_f32_e32 v201, v194
	v_mul_f32_e32 v193, 0x385f10c4, v182
	v_mul_f32_e32 v194, 0.15915494, v193
	v_rndne_f32_e32 v194, v194
	v_fma_f32 v194, v193, 0.15915494, -v194
	v_mul_f32_e32 v194, 0x40c90fdb, v194
	v_mul_f32_e32 v194, 0.15915494, v194
	v_sin_f32_e32 v210, v194
	v_cos_f32_e32 v202, v194
	v_mul_f32_e32 v193, 0x372d07a7, v182
	v_mul_f32_e32 v194, 0.15915494, v193
	v_rndne_f32_e32 v194, v194
	v_fma_f32 v194, v193, 0.15915494, -v194
	v_mul_f32_e32 v194, 0x40c90fdb, v194
	v_mul_f32_e32 v194, 0.15915494, v194
	v_sin_f32_e32 v211, v194
	v_cos_f32_e32 v203, v194
	s_waitcnt lgkmcnt(0)
	v_mul_f32_e32 v204, v204, v184
	v_mul_f32_e32 v196, v196, v96
	v_mul_f32_e32 v204, v204, v192
	v_add_f32_e32 v196, v196, v204
	v_cndmask_b32_e64 v104, v96, v196, s[68:69]
	v_mul_f32_e32 v205, v205, v185
	v_mul_f32_e32 v197, v197, v97
	v_mul_f32_e32 v205, v205, v192
	v_add_f32_e32 v197, v197, v205
	v_cndmask_b32_e64 v105, v97, v197, s[68:69]
	v_mul_f32_e32 v206, v206, v186
	v_mul_f32_e32 v198, v198, v98
	v_mul_f32_e32 v206, v206, v192
	v_add_f32_e32 v198, v198, v206
	v_cndmask_b32_e64 v106, v98, v198, s[68:69]
	v_mul_f32_e32 v207, v207, v187
	v_mul_f32_e32 v199, v199, v99
	v_mul_f32_e32 v207, v207, v192
	v_add_f32_e32 v199, v199, v207
	v_cndmask_b32_e64 v107, v99, v199, s[68:69]
	v_mul_f32_e32 v208, v208, v188
	v_mul_f32_e32 v200, v200, v100
	v_mul_f32_e32 v208, v208, v192
	v_add_f32_e32 v200, v200, v208
	v_cndmask_b32_e64 v108, v100, v200, s[68:69]
	v_mul_f32_e32 v209, v209, v189
	v_mul_f32_e32 v201, v201, v101
	v_mul_f32_e32 v209, v209, v192
	v_add_f32_e32 v201, v201, v209
	v_cndmask_b32_e64 v109, v101, v201, s[68:69]
	v_mul_f32_e32 v210, v210, v190
	v_mul_f32_e32 v202, v202, v102
	v_mul_f32_e32 v210, v210, v192
	v_add_f32_e32 v202, v202, v210
	v_cndmask_b32_e64 v110, v102, v202, s[68:69]
	v_mul_f32_e32 v211, v211, v191
	v_mul_f32_e32 v203, v203, v103
	v_mul_f32_e32 v211, v211, v192
	v_add_f32_e32 v203, v203, v211
	v_cndmask_b32_e64 v111, v103, v203, s[68:69]
	s_branch .LBB0_327

.LBB0_327:
	v_mov_b64_e32 v[100:101], s[78:79]
	v_mad_i64_i32 v[100:101], s[28:29], v112, s26, v[100:101]
	v_cvt_pk_bf16_f32 v96, v104, v105
	v_cvt_pk_bf16_f32 v97, v106, v107
	v_cvt_pk_bf16_f32 v98, v108, v109
	v_cvt_pk_bf16_f32 v99, v110, v111
	v_lshl_add_u64 v[100:101], v[160:161], 1, v[100:101]
	s_and_b64 vcc, exec, s[38:39]
	v_add_u32_e32 v104, 0x80, v181
	global_store_dwordx4 v[100:101], v[96:99], off nt
	s_cbranch_vccnz .LBB0_377
	v_add_u32_e32 v182, 128, v181
	v_xor_b32_e32 v183, 16, v180
	v_and_b32_e32 v182, 0xfff, v182
	v_lshlrev_b32_e32 v183, 2, v183
	v_cvt_f32_u32_e32 v182, v182
	v_cmp_eq_u32_e64 s[60:61], 0, v171
	v_cmp_gt_u32_e64 s[68:69], 2, v171
	ds_bpermute_b32 v184, v183, v88
	ds_bpermute_b32 v185, v183, v89
	ds_bpermute_b32 v186, v183, v90
	ds_bpermute_b32 v187, v183, v91
	ds_bpermute_b32 v188, v183, v92
	ds_bpermute_b32 v189, v183, v93
	ds_bpermute_b32 v190, v183, v94
	ds_bpermute_b32 v191, v183, v95
	v_mov_b32_e32 v192, 1.0
	v_cndmask_b32_e64 v192, v192, -1.0, s[60:61]
	v_mul_f32_e32 v194, 0.15915494, v182
	v_rndne_f32_e32 v194, v194
	v_fma_f32 v194, v182, 0.15915494, -v194
	v_mul_f32_e32 v194, 0x40c90fdb, v194
	v_mul_f32_e32 v194, 0.15915494, v194
	v_sin_f32_e32 v204, v194
	v_cos_f32_e32 v196, v194
	v_mul_f32_e32 v193, 0x3e4693af, v182
	v_mul_f32_e32 v194, 0.15915494, v193
	v_rndne_f32_e32 v194, v194
	v_fma_f32 v194, v193, 0.15915494, -v194
	v_mul_f32_e32 v194, 0x40c90fdb, v194
	v_mul_f32_e32 v194, 0.15915494, v194
	v_sin_f32_e32 v205, v194
	v_cos_f32_e32 v197, v194
	v_mul_f32_e32 v193, 0x3d1a08c8, v182
	v_mul_f32_e32 v194, 0.15915494, v193
	v_rndne_f32_e32 v194, v194
	v_fma_f32 v194, v193, 0.15915494, -v194
	v_mul_f32_e32 v194, 0x40c90fdb, v194
	v_mul_f32_e32 v194, 0.15915494, v194
	v_sin_f32_e32 v206, v194
	v_cos_f32_e32 v198, v194
	v_mul_f32_e32 v193, 0x3beef74e, v182
	v_mul_f32_e32 v194, 0.15915494, v193
	v_rndne_f32_e32 v194, v194
	v_fma_f32 v194, v193, 0.15915494, -v194
	v_mul_f32_e32 v194, 0x40c90fdb, v194
	v_mul_f32_e32 v194, 0.15915494, v194
	v_sin_f32_e32 v207, v194
	v_cos_f32_e32 v199, v194
	v_mul_f32_e32 v193, 0x3ab95d22, v182
	v_mul_f32_e32 v194, 0.15915494, v193
	v_rndne_f32_e32 v194, v194
	v_fma_f32 v194, v193, 0.15915494, -v194
	v_mul_f32_e32 v194, 0x40c90fdb, v194
	v_mul_f32_e32 v194, 0.15915494, v194
	v_sin_f32_e32 v208, v194
	v_cos_f32_e32 v200, v194
	v_mul_f32_e32 v193, 0x398fc8f8, v182
	v_mul_f32_e32 v194, 0.15915494, v193
	v_rndne_f32_e32 v194, v194
	v_fma_f32 v194, v193, 0.15915494, -v194
	v_mul_f32_e32 v194, 0x40c90fdb, v194
	v_mul_f32_e32 v194, 0.15915494, v194
	v_sin_f32_e32 v209, v194
	v_cos_f32_e32 v201, v194
	v_mul_f32_e32 v193, 0x385f10c4, v182
	v_mul_f32_e32 v194, 0.15915494, v193
	v_rndne_f32_e32 v194, v194
	v_fma_f32 v194, v193, 0.15915494, -v194
	v_mul_f32_e32 v194, 0x40c90fdb, v194
	v_mul_f32_e32 v194, 0.15915494, v194
	v_sin_f32_e32 v210, v194
	v_cos_f32_e32 v202, v194
	v_mul_f32_e32 v193, 0x372d07a7, v182
	v_mul_f32_e32 v194, 0.15915494, v193
	v_rndne_f32_e32 v194, v194
	v_fma_f32 v194, v193, 0.15915494, -v194
	v_mul_f32_e32 v194, 0x40c90fdb, v194
	v_mul_f32_e32 v194, 0.15915494, v194
	v_sin_f32_e32 v211, v194
	v_cos_f32_e32 v203, v194
	s_waitcnt lgkmcnt(0)
	v_mul_f32_e32 v204, v204, v184
	v_mul_f32_e32 v196, v196, v88
	v_mul_f32_e32 v204, v204, v192
	v_add_f32_e32 v196, v196, v204
	v_cndmask_b32_e64 v96, v88, v196, s[68:69]
	v_mul_f32_e32 v205, v205, v185
	v_mul_f32_e32 v197, v197, v89
	v_mul_f32_e32 v205, v205, v192
	v_add_f32_e32 v197, v197, v205
	v_cndmask_b32_e64 v97, v89, v197, s[68:69]
	v_mul_f32_e32 v206, v206, v186
	v_mul_f32_e32 v198, v198, v90
	v_mul_f32_e32 v206, v206, v192
	v_add_f32_e32 v198, v198, v206
	v_cndmask_b32_e64 v98, v90, v198, s[68:69]
	v_mul_f32_e32 v207, v207, v187
	v_mul_f32_e32 v199, v199, v91
	v_mul_f32_e32 v207, v207, v192
	v_add_f32_e32 v199, v199, v207
	v_cndmask_b32_e64 v99, v91, v199, s[68:69]
	v_mul_f32_e32 v208, v208, v188
	v_mul_f32_e32 v200, v200, v92
	v_mul_f32_e32 v208, v208, v192
	v_add_f32_e32 v200, v200, v208
	v_cndmask_b32_e64 v100, v92, v200, s[68:69]
	v_mul_f32_e32 v209, v209, v189
	v_mul_f32_e32 v201, v201, v93
	v_mul_f32_e32 v209, v209, v192
	v_add_f32_e32 v201, v201, v209
	v_cndmask_b32_e64 v101, v93, v201, s[68:69]
	v_mul_f32_e32 v210, v210, v190
	v_mul_f32_e32 v202, v202, v94
	v_mul_f32_e32 v210, v210, v192
	v_add_f32_e32 v202, v202, v210
	v_cndmask_b32_e64 v102, v94, v202, s[68:69]
	v_mul_f32_e32 v211, v211, v191
	v_mul_f32_e32 v203, v203, v95
	v_mul_f32_e32 v211, v211, v192
	v_add_f32_e32 v203, v203, v211
	v_cndmask_b32_e64 v103, v95, v203, s[68:69]
	s_branch .LBB0_378

.LBB0_378:
	v_mov_b64_e32 v[92:93], s[78:79]
	v_mad_i64_i32 v[92:93], s[28:29], v104, s26, v[92:93]
	v_cvt_pk_bf16_f32 v88, v96, v97
	v_cvt_pk_bf16_f32 v89, v98, v99
	v_cvt_pk_bf16_f32 v90, v100, v101
	v_cvt_pk_bf16_f32 v91, v102, v103
	v_lshl_add_u64 v[92:93], v[160:161], 1, v[92:93]
	s_and_b64 vcc, exec, s[38:39]
	v_add_u32_e32 v96, 0x90, v181
	global_store_dwordx4 v[92:93], v[88:91], off nt
	s_cbranch_vccnz .LBB0_428
	v_add_u32_e32 v182, 144, v181
	v_xor_b32_e32 v183, 16, v180
	v_and_b32_e32 v182, 0xfff, v182
	v_lshlrev_b32_e32 v183, 2, v183
	v_cvt_f32_u32_e32 v182, v182
	v_cmp_eq_u32_e64 s[60:61], 0, v171
	v_cmp_gt_u32_e64 s[68:69], 2, v171
	ds_bpermute_b32 v184, v183, v80
	ds_bpermute_b32 v185, v183, v81
	ds_bpermute_b32 v186, v183, v82
	ds_bpermute_b32 v187, v183, v83
	ds_bpermute_b32 v188, v183, v84
	ds_bpermute_b32 v189, v183, v85
	ds_bpermute_b32 v190, v183, v86
	ds_bpermute_b32 v191, v183, v87
	v_mov_b32_e32 v192, 1.0
	v_cndmask_b32_e64 v192, v192, -1.0, s[60:61]
	v_mul_f32_e32 v194, 0.15915494, v182
	v_rndne_f32_e32 v194, v194
	v_fma_f32 v194, v182, 0.15915494, -v194
	v_mul_f32_e32 v194, 0x40c90fdb, v194
	v_mul_f32_e32 v194, 0.15915494, v194
	v_sin_f32_e32 v204, v194
	v_cos_f32_e32 v196, v194
	v_mul_f32_e32 v193, 0x3e4693af, v182
	v_mul_f32_e32 v194, 0.15915494, v193
	v_rndne_f32_e32 v194, v194
	v_fma_f32 v194, v193, 0.15915494, -v194
	v_mul_f32_e32 v194, 0x40c90fdb, v194
	v_mul_f32_e32 v194, 0.15915494, v194
	v_sin_f32_e32 v205, v194
	v_cos_f32_e32 v197, v194
	v_mul_f32_e32 v193, 0x3d1a08c8, v182
	v_mul_f32_e32 v194, 0.15915494, v193
	v_rndne_f32_e32 v194, v194
	v_fma_f32 v194, v193, 0.15915494, -v194
	v_mul_f32_e32 v194, 0x40c90fdb, v194
	v_mul_f32_e32 v194, 0.15915494, v194
	v_sin_f32_e32 v206, v194
	v_cos_f32_e32 v198, v194
	v_mul_f32_e32 v193, 0x3beef74e, v182
	v_mul_f32_e32 v194, 0.15915494, v193
	v_rndne_f32_e32 v194, v194
	v_fma_f32 v194, v193, 0.15915494, -v194
	v_mul_f32_e32 v194, 0x40c90fdb, v194
	v_mul_f32_e32 v194, 0.15915494, v194
	v_sin_f32_e32 v207, v194
	v_cos_f32_e32 v199, v194
	v_mul_f32_e32 v193, 0x3ab95d22, v182
	v_mul_f32_e32 v194, 0.15915494, v193
	v_rndne_f32_e32 v194, v194
	v_fma_f32 v194, v193, 0.15915494, -v194
	v_mul_f32_e32 v194, 0x40c90fdb, v194
	v_mul_f32_e32 v194, 0.15915494, v194
	v_sin_f32_e32 v208, v194
	v_cos_f32_e32 v200, v194
	v_mul_f32_e32 v193, 0x398fc8f8, v182
	v_mul_f32_e32 v194, 0.15915494, v193
	v_rndne_f32_e32 v194, v194
	v_fma_f32 v194, v193, 0.15915494, -v194
	v_mul_f32_e32 v194, 0x40c90fdb, v194
	v_mul_f32_e32 v194, 0.15915494, v194
	v_sin_f32_e32 v209, v194
	v_cos_f32_e32 v201, v194
	v_mul_f32_e32 v193, 0x385f10c4, v182
	v_mul_f32_e32 v194, 0.15915494, v193
	v_rndne_f32_e32 v194, v194
	v_fma_f32 v194, v193, 0.15915494, -v194
	v_mul_f32_e32 v194, 0x40c90fdb, v194
	v_mul_f32_e32 v194, 0.15915494, v194
	v_sin_f32_e32 v210, v194
	v_cos_f32_e32 v202, v194
	v_mul_f32_e32 v193, 0x372d07a7, v182
	v_mul_f32_e32 v194, 0.15915494, v193
	v_rndne_f32_e32 v194, v194
	v_fma_f32 v194, v193, 0.15915494, -v194
	v_mul_f32_e32 v194, 0x40c90fdb, v194
	v_mul_f32_e32 v194, 0.15915494, v194
	v_sin_f32_e32 v211, v194
	v_cos_f32_e32 v203, v194
	s_waitcnt lgkmcnt(0)
	v_mul_f32_e32 v204, v204, v184
	v_mul_f32_e32 v196, v196, v80
	v_mul_f32_e32 v204, v204, v192
	v_add_f32_e32 v196, v196, v204
	v_cndmask_b32_e64 v88, v80, v196, s[68:69]
	v_mul_f32_e32 v205, v205, v185
	v_mul_f32_e32 v197, v197, v81
	v_mul_f32_e32 v205, v205, v192
	v_add_f32_e32 v197, v197, v205
	v_cndmask_b32_e64 v89, v81, v197, s[68:69]
	v_mul_f32_e32 v206, v206, v186
	v_mul_f32_e32 v198, v198, v82
	v_mul_f32_e32 v206, v206, v192
	v_add_f32_e32 v198, v198, v206
	v_cndmask_b32_e64 v90, v82, v198, s[68:69]
	v_mul_f32_e32 v207, v207, v187
	v_mul_f32_e32 v199, v199, v83
	v_mul_f32_e32 v207, v207, v192
	v_add_f32_e32 v199, v199, v207
	v_cndmask_b32_e64 v91, v83, v199, s[68:69]
	v_mul_f32_e32 v208, v208, v188
	v_mul_f32_e32 v200, v200, v84
	v_mul_f32_e32 v208, v208, v192
	v_add_f32_e32 v200, v200, v208
	v_cndmask_b32_e64 v92, v84, v200, s[68:69]
	v_mul_f32_e32 v209, v209, v189
	v_mul_f32_e32 v201, v201, v85
	v_mul_f32_e32 v209, v209, v192
	v_add_f32_e32 v201, v201, v209
	v_cndmask_b32_e64 v93, v85, v201, s[68:69]
	v_mul_f32_e32 v210, v210, v190
	v_mul_f32_e32 v202, v202, v86
	v_mul_f32_e32 v210, v210, v192
	v_add_f32_e32 v202, v202, v210
	v_cndmask_b32_e64 v94, v86, v202, s[68:69]
	v_mul_f32_e32 v211, v211, v191
	v_mul_f32_e32 v203, v203, v87
	v_mul_f32_e32 v211, v211, v192
	v_add_f32_e32 v203, v203, v211
	v_cndmask_b32_e64 v95, v87, v203, s[68:69]
	s_branch .LBB0_429

.LBB0_429:
	v_mov_b64_e32 v[84:85], s[78:79]
	v_mad_i64_i32 v[84:85], s[28:29], v96, s26, v[84:85]
	v_cvt_pk_bf16_f32 v80, v88, v89
	v_cvt_pk_bf16_f32 v81, v90, v91
	v_cvt_pk_bf16_f32 v82, v92, v93
	v_cvt_pk_bf16_f32 v83, v94, v95
	v_lshl_add_u64 v[84:85], v[160:161], 1, v[84:85]
	s_and_b64 vcc, exec, s[38:39]
	v_add_u32_e32 v88, 0xa0, v181
	global_store_dwordx4 v[84:85], v[80:83], off nt
	s_cbranch_vccnz .LBB0_479
	v_add_u32_e32 v182, 160, v181
	v_xor_b32_e32 v183, 16, v180
	v_and_b32_e32 v182, 0xfff, v182
	v_lshlrev_b32_e32 v183, 2, v183
	v_cvt_f32_u32_e32 v182, v182
	v_cmp_eq_u32_e64 s[60:61], 0, v171
	v_cmp_gt_u32_e64 s[68:69], 2, v171
	ds_bpermute_b32 v184, v183, v72
	ds_bpermute_b32 v185, v183, v73
	ds_bpermute_b32 v186, v183, v74
	ds_bpermute_b32 v187, v183, v75
	ds_bpermute_b32 v188, v183, v76
	ds_bpermute_b32 v189, v183, v77
	ds_bpermute_b32 v190, v183, v78
	ds_bpermute_b32 v191, v183, v79
	v_mov_b32_e32 v192, 1.0
	v_cndmask_b32_e64 v192, v192, -1.0, s[60:61]
	v_mul_f32_e32 v194, 0.15915494, v182
	v_rndne_f32_e32 v194, v194
	v_fma_f32 v194, v182, 0.15915494, -v194
	v_mul_f32_e32 v194, 0x40c90fdb, v194
	v_mul_f32_e32 v194, 0.15915494, v194
	v_sin_f32_e32 v204, v194
	v_cos_f32_e32 v196, v194
	v_mul_f32_e32 v193, 0x3e4693af, v182
	v_mul_f32_e32 v194, 0.15915494, v193
	v_rndne_f32_e32 v194, v194
	v_fma_f32 v194, v193, 0.15915494, -v194
	v_mul_f32_e32 v194, 0x40c90fdb, v194
	v_mul_f32_e32 v194, 0.15915494, v194
	v_sin_f32_e32 v205, v194
	v_cos_f32_e32 v197, v194
	v_mul_f32_e32 v193, 0x3d1a08c8, v182
	v_mul_f32_e32 v194, 0.15915494, v193
	v_rndne_f32_e32 v194, v194
	v_fma_f32 v194, v193, 0.15915494, -v194
	v_mul_f32_e32 v194, 0x40c90fdb, v194
	v_mul_f32_e32 v194, 0.15915494, v194
	v_sin_f32_e32 v206, v194
	v_cos_f32_e32 v198, v194
	v_mul_f32_e32 v193, 0x3beef74e, v182
	v_mul_f32_e32 v194, 0.15915494, v193
	v_rndne_f32_e32 v194, v194
	v_fma_f32 v194, v193, 0.15915494, -v194
	v_mul_f32_e32 v194, 0x40c90fdb, v194
	v_mul_f32_e32 v194, 0.15915494, v194
	v_sin_f32_e32 v207, v194
	v_cos_f32_e32 v199, v194
	v_mul_f32_e32 v193, 0x3ab95d22, v182
	v_mul_f32_e32 v194, 0.15915494, v193
	v_rndne_f32_e32 v194, v194
	v_fma_f32 v194, v193, 0.15915494, -v194
	v_mul_f32_e32 v194, 0x40c90fdb, v194
	v_mul_f32_e32 v194, 0.15915494, v194
	v_sin_f32_e32 v208, v194
	v_cos_f32_e32 v200, v194
	v_mul_f32_e32 v193, 0x398fc8f8, v182
	v_mul_f32_e32 v194, 0.15915494, v193
	v_rndne_f32_e32 v194, v194
	v_fma_f32 v194, v193, 0.15915494, -v194
	v_mul_f32_e32 v194, 0x40c90fdb, v194
	v_mul_f32_e32 v194, 0.15915494, v194
	v_sin_f32_e32 v209, v194
	v_cos_f32_e32 v201, v194
	v_mul_f32_e32 v193, 0x385f10c4, v182
	v_mul_f32_e32 v194, 0.15915494, v193
	v_rndne_f32_e32 v194, v194
	v_fma_f32 v194, v193, 0.15915494, -v194
	v_mul_f32_e32 v194, 0x40c90fdb, v194
	v_mul_f32_e32 v194, 0.15915494, v194
	v_sin_f32_e32 v210, v194
	v_cos_f32_e32 v202, v194
	v_mul_f32_e32 v193, 0x372d07a7, v182
	v_mul_f32_e32 v194, 0.15915494, v193
	v_rndne_f32_e32 v194, v194
	v_fma_f32 v194, v193, 0.15915494, -v194
	v_mul_f32_e32 v194, 0x40c90fdb, v194
	v_mul_f32_e32 v194, 0.15915494, v194
	v_sin_f32_e32 v211, v194
	v_cos_f32_e32 v203, v194
	s_waitcnt lgkmcnt(0)
	v_mul_f32_e32 v204, v204, v184
	v_mul_f32_e32 v196, v196, v72
	v_mul_f32_e32 v204, v204, v192
	v_add_f32_e32 v196, v196, v204
	v_cndmask_b32_e64 v80, v72, v196, s[68:69]
	v_mul_f32_e32 v205, v205, v185
	v_mul_f32_e32 v197, v197, v73
	v_mul_f32_e32 v205, v205, v192
	v_add_f32_e32 v197, v197, v205
	v_cndmask_b32_e64 v81, v73, v197, s[68:69]
	v_mul_f32_e32 v206, v206, v186
	v_mul_f32_e32 v198, v198, v74
	v_mul_f32_e32 v206, v206, v192
	v_add_f32_e32 v198, v198, v206
	v_cndmask_b32_e64 v82, v74, v198, s[68:69]
	v_mul_f32_e32 v207, v207, v187
	v_mul_f32_e32 v199, v199, v75
	v_mul_f32_e32 v207, v207, v192
	v_add_f32_e32 v199, v199, v207
	v_cndmask_b32_e64 v83, v75, v199, s[68:69]
	v_mul_f32_e32 v208, v208, v188
	v_mul_f32_e32 v200, v200, v76
	v_mul_f32_e32 v208, v208, v192
	v_add_f32_e32 v200, v200, v208
	v_cndmask_b32_e64 v84, v76, v200, s[68:69]
	v_mul_f32_e32 v209, v209, v189
	v_mul_f32_e32 v201, v201, v77
	v_mul_f32_e32 v209, v209, v192
	v_add_f32_e32 v201, v201, v209
	v_cndmask_b32_e64 v85, v77, v201, s[68:69]
	v_mul_f32_e32 v210, v210, v190
	v_mul_f32_e32 v202, v202, v78
	v_mul_f32_e32 v210, v210, v192
	v_add_f32_e32 v202, v202, v210
	v_cndmask_b32_e64 v86, v78, v202, s[68:69]
	v_mul_f32_e32 v211, v211, v191
	v_mul_f32_e32 v203, v203, v79
	v_mul_f32_e32 v211, v211, v192
	v_add_f32_e32 v203, v203, v211
	v_cndmask_b32_e64 v87, v79, v203, s[68:69]
	s_branch .LBB0_480

.LBB0_480:
	v_mov_b64_e32 v[76:77], s[78:79]
	v_mad_i64_i32 v[76:77], s[28:29], v88, s26, v[76:77]
	v_cvt_pk_bf16_f32 v72, v80, v81
	v_cvt_pk_bf16_f32 v73, v82, v83
	v_cvt_pk_bf16_f32 v74, v84, v85
	v_cvt_pk_bf16_f32 v75, v86, v87
	v_lshl_add_u64 v[76:77], v[160:161], 1, v[76:77]
	s_and_b64 vcc, exec, s[38:39]
	v_add_u32_e32 v80, 0xb0, v181
	global_store_dwordx4 v[76:77], v[72:75], off nt
	s_cbranch_vccnz .LBB0_530
	v_add_u32_e32 v182, 176, v181
	v_xor_b32_e32 v183, 16, v180
	v_and_b32_e32 v182, 0xfff, v182
	v_lshlrev_b32_e32 v183, 2, v183
	v_cvt_f32_u32_e32 v182, v182
	v_cmp_eq_u32_e64 s[60:61], 0, v171
	v_cmp_gt_u32_e64 s[68:69], 2, v171
	ds_bpermute_b32 v184, v183, v64
	ds_bpermute_b32 v185, v183, v65
	ds_bpermute_b32 v186, v183, v66
	ds_bpermute_b32 v187, v183, v67
	ds_bpermute_b32 v188, v183, v68
	ds_bpermute_b32 v189, v183, v69
	ds_bpermute_b32 v190, v183, v70
	ds_bpermute_b32 v191, v183, v71
	v_mov_b32_e32 v192, 1.0
	v_cndmask_b32_e64 v192, v192, -1.0, s[60:61]
	v_mul_f32_e32 v194, 0.15915494, v182
	v_rndne_f32_e32 v194, v194
	v_fma_f32 v194, v182, 0.15915494, -v194
	v_mul_f32_e32 v194, 0x40c90fdb, v194
	v_mul_f32_e32 v194, 0.15915494, v194
	v_sin_f32_e32 v204, v194
	v_cos_f32_e32 v196, v194
	v_mul_f32_e32 v193, 0x3e4693af, v182
	v_mul_f32_e32 v194, 0.15915494, v193
	v_rndne_f32_e32 v194, v194
	v_fma_f32 v194, v193, 0.15915494, -v194
	v_mul_f32_e32 v194, 0x40c90fdb, v194
	v_mul_f32_e32 v194, 0.15915494, v194
	v_sin_f32_e32 v205, v194
	v_cos_f32_e32 v197, v194
	v_mul_f32_e32 v193, 0x3d1a08c8, v182
	v_mul_f32_e32 v194, 0.15915494, v193
	v_rndne_f32_e32 v194, v194
	v_fma_f32 v194, v193, 0.15915494, -v194
	v_mul_f32_e32 v194, 0x40c90fdb, v194
	v_mul_f32_e32 v194, 0.15915494, v194
	v_sin_f32_e32 v206, v194
	v_cos_f32_e32 v198, v194
	v_mul_f32_e32 v193, 0x3beef74e, v182
	v_mul_f32_e32 v194, 0.15915494, v193
	v_rndne_f32_e32 v194, v194
	v_fma_f32 v194, v193, 0.15915494, -v194
	v_mul_f32_e32 v194, 0x40c90fdb, v194
	v_mul_f32_e32 v194, 0.15915494, v194
	v_sin_f32_e32 v207, v194
	v_cos_f32_e32 v199, v194
	v_mul_f32_e32 v193, 0x3ab95d22, v182
	v_mul_f32_e32 v194, 0.15915494, v193
	v_rndne_f32_e32 v194, v194
	v_fma_f32 v194, v193, 0.15915494, -v194
	v_mul_f32_e32 v194, 0x40c90fdb, v194
	v_mul_f32_e32 v194, 0.15915494, v194
	v_sin_f32_e32 v208, v194
	v_cos_f32_e32 v200, v194
	v_mul_f32_e32 v193, 0x398fc8f8, v182
	v_mul_f32_e32 v194, 0.15915494, v193
	v_rndne_f32_e32 v194, v194
	v_fma_f32 v194, v193, 0.15915494, -v194
	v_mul_f32_e32 v194, 0x40c90fdb, v194
	v_mul_f32_e32 v194, 0.15915494, v194
	v_sin_f32_e32 v209, v194
	v_cos_f32_e32 v201, v194
	v_mul_f32_e32 v193, 0x385f10c4, v182
	v_mul_f32_e32 v194, 0.15915494, v193
	v_rndne_f32_e32 v194, v194
	v_fma_f32 v194, v193, 0.15915494, -v194
	v_mul_f32_e32 v194, 0x40c90fdb, v194
	v_mul_f32_e32 v194, 0.15915494, v194
	v_sin_f32_e32 v210, v194
	v_cos_f32_e32 v202, v194
	v_mul_f32_e32 v193, 0x372d07a7, v182
	v_mul_f32_e32 v194, 0.15915494, v193
	v_rndne_f32_e32 v194, v194
	v_fma_f32 v194, v193, 0.15915494, -v194
	v_mul_f32_e32 v194, 0x40c90fdb, v194
	v_mul_f32_e32 v194, 0.15915494, v194
	v_sin_f32_e32 v211, v194
	v_cos_f32_e32 v203, v194
	s_waitcnt lgkmcnt(0)
	v_mul_f32_e32 v204, v204, v184
	v_mul_f32_e32 v196, v196, v64
	v_mul_f32_e32 v204, v204, v192
	v_add_f32_e32 v196, v196, v204
	v_cndmask_b32_e64 v72, v64, v196, s[68:69]
	v_mul_f32_e32 v205, v205, v185
	v_mul_f32_e32 v197, v197, v65
	v_mul_f32_e32 v205, v205, v192
	v_add_f32_e32 v197, v197, v205
	v_cndmask_b32_e64 v73, v65, v197, s[68:69]
	v_mul_f32_e32 v206, v206, v186
	v_mul_f32_e32 v198, v198, v66
	v_mul_f32_e32 v206, v206, v192
	v_add_f32_e32 v198, v198, v206
	v_cndmask_b32_e64 v74, v66, v198, s[68:69]
	v_mul_f32_e32 v207, v207, v187
	v_mul_f32_e32 v199, v199, v67
	v_mul_f32_e32 v207, v207, v192
	v_add_f32_e32 v199, v199, v207
	v_cndmask_b32_e64 v75, v67, v199, s[68:69]
	v_mul_f32_e32 v208, v208, v188
	v_mul_f32_e32 v200, v200, v68
	v_mul_f32_e32 v208, v208, v192
	v_add_f32_e32 v200, v200, v208
	v_cndmask_b32_e64 v76, v68, v200, s[68:69]
	v_mul_f32_e32 v209, v209, v189
	v_mul_f32_e32 v201, v201, v69
	v_mul_f32_e32 v209, v209, v192
	v_add_f32_e32 v201, v201, v209
	v_cndmask_b32_e64 v77, v69, v201, s[68:69]
	v_mul_f32_e32 v210, v210, v190
	v_mul_f32_e32 v202, v202, v70
	v_mul_f32_e32 v210, v210, v192
	v_add_f32_e32 v202, v202, v210
	v_cndmask_b32_e64 v78, v70, v202, s[68:69]
	v_mul_f32_e32 v211, v211, v191
	v_mul_f32_e32 v203, v203, v71
	v_mul_f32_e32 v211, v211, v192
	v_add_f32_e32 v203, v203, v211
	v_cndmask_b32_e64 v79, v71, v203, s[68:69]
	s_branch .LBB0_531

.LBB0_532:
	s_addk_i32 s27, 0xfa00
	s_cmpk_lt_u32 s27, 0x400
	s_cselect_b64 s[28:29], -1, 0
	s_and_b64 s[28:29], s[44:45], s[28:29]
	v_cndmask_b32_e64 v64, 0, 1, s[28:29]
	v_cmp_ne_u32_e64 s[38:39], 1, v64
	s_andn2_b64 vcc, exec, s[28:29]
	s_cbranch_vccnz .LBB0_582
	v_mov_b32_e32 v182, v181
	v_xor_b32_e32 v183, 16, v180
	v_and_b32_e32 v182, 0xfff, v182
	v_lshlrev_b32_e32 v183, 2, v183
	v_cvt_f32_u32_e32 v182, v182
	v_cmp_eq_u32_e64 s[60:61], 0, v171
	v_cmp_gt_u32_e64 s[68:69], 2, v171
	ds_bpermute_b32 v184, v183, v56
	ds_bpermute_b32 v185, v183, v57
	ds_bpermute_b32 v186, v183, v58
	ds_bpermute_b32 v187, v183, v59
	ds_bpermute_b32 v188, v183, v60
	ds_bpermute_b32 v189, v183, v61
	ds_bpermute_b32 v190, v183, v62
	ds_bpermute_b32 v191, v183, v63
	v_mov_b32_e32 v192, 1.0
	v_cndmask_b32_e64 v192, v192, -1.0, s[60:61]
	v_mul_f32_e32 v194, 0.15915494, v182
	v_rndne_f32_e32 v194, v194
	v_fma_f32 v194, v182, 0.15915494, -v194
	v_mul_f32_e32 v194, 0x40c90fdb, v194
	v_mul_f32_e32 v194, 0.15915494, v194
	v_sin_f32_e32 v204, v194
	v_cos_f32_e32 v196, v194
	v_mul_f32_e32 v193, 0x3e4693af, v182
	v_mul_f32_e32 v194, 0.15915494, v193
	v_rndne_f32_e32 v194, v194
	v_fma_f32 v194, v193, 0.15915494, -v194
	v_mul_f32_e32 v194, 0x40c90fdb, v194
	v_mul_f32_e32 v194, 0.15915494, v194
	v_sin_f32_e32 v205, v194
	v_cos_f32_e32 v197, v194
	v_mul_f32_e32 v193, 0x3d1a08c8, v182
	v_mul_f32_e32 v194, 0.15915494, v193
	v_rndne_f32_e32 v194, v194
	v_fma_f32 v194, v193, 0.15915494, -v194
	v_mul_f32_e32 v194, 0x40c90fdb, v194
	v_mul_f32_e32 v194, 0.15915494, v194
	v_sin_f32_e32 v206, v194
	v_cos_f32_e32 v198, v194
	v_mul_f32_e32 v193, 0x3beef74e, v182
	v_mul_f32_e32 v194, 0.15915494, v193
	v_rndne_f32_e32 v194, v194
	v_fma_f32 v194, v193, 0.15915494, -v194
	v_mul_f32_e32 v194, 0x40c90fdb, v194
	v_mul_f32_e32 v194, 0.15915494, v194
	v_sin_f32_e32 v207, v194
	v_cos_f32_e32 v199, v194
	v_mul_f32_e32 v193, 0x3ab95d22, v182
	v_mul_f32_e32 v194, 0.15915494, v193
	v_rndne_f32_e32 v194, v194
	v_fma_f32 v194, v193, 0.15915494, -v194
	v_mul_f32_e32 v194, 0x40c90fdb, v194
	v_mul_f32_e32 v194, 0.15915494, v194
	v_sin_f32_e32 v208, v194
	v_cos_f32_e32 v200, v194
	v_mul_f32_e32 v193, 0x398fc8f8, v182
	v_mul_f32_e32 v194, 0.15915494, v193
	v_rndne_f32_e32 v194, v194
	v_fma_f32 v194, v193, 0.15915494, -v194
	v_mul_f32_e32 v194, 0x40c90fdb, v194
	v_mul_f32_e32 v194, 0.15915494, v194
	v_sin_f32_e32 v209, v194
	v_cos_f32_e32 v201, v194
	v_mul_f32_e32 v193, 0x385f10c4, v182
	v_mul_f32_e32 v194, 0.15915494, v193
	v_rndne_f32_e32 v194, v194
	v_fma_f32 v194, v193, 0.15915494, -v194
	v_mul_f32_e32 v194, 0x40c90fdb, v194
	v_mul_f32_e32 v194, 0.15915494, v194
	v_sin_f32_e32 v210, v194
	v_cos_f32_e32 v202, v194
	v_mul_f32_e32 v193, 0x372d07a7, v182
	v_mul_f32_e32 v194, 0.15915494, v193
	v_rndne_f32_e32 v194, v194
	v_fma_f32 v194, v193, 0.15915494, -v194
	v_mul_f32_e32 v194, 0x40c90fdb, v194
	v_mul_f32_e32 v194, 0.15915494, v194
	v_sin_f32_e32 v211, v194
	v_cos_f32_e32 v203, v194
	s_waitcnt lgkmcnt(0)
	v_mul_f32_e32 v204, v204, v184
	v_mul_f32_e32 v196, v196, v56
	v_mul_f32_e32 v204, v204, v192
	v_add_f32_e32 v196, v196, v204
	v_cndmask_b32_e64 v64, v56, v196, s[68:69]
	v_mul_f32_e32 v205, v205, v185
	v_mul_f32_e32 v197, v197, v57
	v_mul_f32_e32 v205, v205, v192
	v_add_f32_e32 v197, v197, v205
	v_cndmask_b32_e64 v65, v57, v197, s[68:69]
	v_mul_f32_e32 v206, v206, v186
	v_mul_f32_e32 v198, v198, v58
	v_mul_f32_e32 v206, v206, v192
	v_add_f32_e32 v198, v198, v206
	v_cndmask_b32_e64 v66, v58, v198, s[68:69]
	v_mul_f32_e32 v207, v207, v187
	v_mul_f32_e32 v199, v199, v59
	v_mul_f32_e32 v207, v207, v192
	v_add_f32_e32 v199, v199, v207
	v_cndmask_b32_e64 v67, v59, v199, s[68:69]
	v_mul_f32_e32 v208, v208, v188
	v_mul_f32_e32 v200, v200, v60
	v_mul_f32_e32 v208, v208, v192
	v_add_f32_e32 v200, v200, v208
	v_cndmask_b32_e64 v68, v60, v200, s[68:69]
	v_mul_f32_e32 v209, v209, v189
	v_mul_f32_e32 v201, v201, v61
	v_mul_f32_e32 v209, v209, v192
	v_add_f32_e32 v201, v201, v209
	v_cndmask_b32_e64 v69, v61, v201, s[68:69]
	v_mul_f32_e32 v210, v210, v190
	v_mul_f32_e32 v202, v202, v62
	v_mul_f32_e32 v210, v210, v192
	v_add_f32_e32 v202, v202, v210
	v_cndmask_b32_e64 v70, v62, v202, s[68:69]
	v_mul_f32_e32 v211, v211, v191
	v_mul_f32_e32 v203, v203, v63
	v_mul_f32_e32 v211, v211, v192
	v_add_f32_e32 v203, v203, v211
	v_cndmask_b32_e64 v71, v63, v203, s[68:69]
	s_branch .LBB0_583

.LBB0_583:
	v_mov_b64_e32 v[60:61], s[78:79]
	s_ashr_i32 s55, s54, 31
	v_cvt_pk_bf16_f32 v56, v64, v65
	v_mad_i64_i32 v[60:61], s[28:29], v181, s26, v[60:61]
	v_lshl_add_u64 v[64:65], s[54:55], 0, v[150:151]
	v_cvt_pk_bf16_f32 v57, v66, v67
	v_cvt_pk_bf16_f32 v58, v68, v69
	v_cvt_pk_bf16_f32 v59, v70, v71
	v_lshl_add_u64 v[60:61], v[64:65], 1, v[60:61]
	s_and_b64 vcc, exec, s[38:39]
	v_or_b32_e32 v66, 16, v181
	global_store_dwordx4 v[60:61], v[56:59], off offset:256 nt
	s_cbranch_vccnz .LBB0_633
	v_add_u32_e32 v182, 16, v181
	v_xor_b32_e32 v183, 16, v180
	v_and_b32_e32 v182, 0xfff, v182
	v_lshlrev_b32_e32 v183, 2, v183
	v_cvt_f32_u32_e32 v182, v182
	v_cmp_eq_u32_e64 s[60:61], 0, v171
	v_cmp_gt_u32_e64 s[68:69], 2, v171
	ds_bpermute_b32 v184, v183, v48
	ds_bpermute_b32 v185, v183, v49
	ds_bpermute_b32 v186, v183, v50
	ds_bpermute_b32 v187, v183, v51
	ds_bpermute_b32 v188, v183, v52
	ds_bpermute_b32 v189, v183, v53
	ds_bpermute_b32 v190, v183, v54
	ds_bpermute_b32 v191, v183, v55
	v_mov_b32_e32 v192, 1.0
	v_cndmask_b32_e64 v192, v192, -1.0, s[60:61]
	v_mul_f32_e32 v194, 0.15915494, v182
	v_rndne_f32_e32 v194, v194
	v_fma_f32 v194, v182, 0.15915494, -v194
	v_mul_f32_e32 v194, 0x40c90fdb, v194
	v_mul_f32_e32 v194, 0.15915494, v194
	v_sin_f32_e32 v204, v194
	v_cos_f32_e32 v196, v194
	v_mul_f32_e32 v193, 0x3e4693af, v182
	v_mul_f32_e32 v194, 0.15915494, v193
	v_rndne_f32_e32 v194, v194
	v_fma_f32 v194, v193, 0.15915494, -v194
	v_mul_f32_e32 v194, 0x40c90fdb, v194
	v_mul_f32_e32 v194, 0.15915494, v194
	v_sin_f32_e32 v205, v194
	v_cos_f32_e32 v197, v194
	v_mul_f32_e32 v193, 0x3d1a08c8, v182
	v_mul_f32_e32 v194, 0.15915494, v193
	v_rndne_f32_e32 v194, v194
	v_fma_f32 v194, v193, 0.15915494, -v194
	v_mul_f32_e32 v194, 0x40c90fdb, v194
	v_mul_f32_e32 v194, 0.15915494, v194
	v_sin_f32_e32 v206, v194
	v_cos_f32_e32 v198, v194
	v_mul_f32_e32 v193, 0x3beef74e, v182
	v_mul_f32_e32 v194, 0.15915494, v193
	v_rndne_f32_e32 v194, v194
	v_fma_f32 v194, v193, 0.15915494, -v194
	v_mul_f32_e32 v194, 0x40c90fdb, v194
	v_mul_f32_e32 v194, 0.15915494, v194
	v_sin_f32_e32 v207, v194
	v_cos_f32_e32 v199, v194
	v_mul_f32_e32 v193, 0x3ab95d22, v182
	v_mul_f32_e32 v194, 0.15915494, v193
	v_rndne_f32_e32 v194, v194
	v_fma_f32 v194, v193, 0.15915494, -v194
	v_mul_f32_e32 v194, 0x40c90fdb, v194
	v_mul_f32_e32 v194, 0.15915494, v194
	v_sin_f32_e32 v208, v194
	v_cos_f32_e32 v200, v194
	v_mul_f32_e32 v193, 0x398fc8f8, v182
	v_mul_f32_e32 v194, 0.15915494, v193
	v_rndne_f32_e32 v194, v194
	v_fma_f32 v194, v193, 0.15915494, -v194
	v_mul_f32_e32 v194, 0x40c90fdb, v194
	v_mul_f32_e32 v194, 0.15915494, v194
	v_sin_f32_e32 v209, v194
	v_cos_f32_e32 v201, v194
	v_mul_f32_e32 v193, 0x385f10c4, v182
	v_mul_f32_e32 v194, 0.15915494, v193
	v_rndne_f32_e32 v194, v194
	v_fma_f32 v194, v193, 0.15915494, -v194
	v_mul_f32_e32 v194, 0x40c90fdb, v194
	v_mul_f32_e32 v194, 0.15915494, v194
	v_sin_f32_e32 v210, v194
	v_cos_f32_e32 v202, v194
	v_mul_f32_e32 v193, 0x372d07a7, v182
	v_mul_f32_e32 v194, 0.15915494, v193
	v_rndne_f32_e32 v194, v194
	v_fma_f32 v194, v193, 0.15915494, -v194
	v_mul_f32_e32 v194, 0x40c90fdb, v194
	v_mul_f32_e32 v194, 0.15915494, v194
	v_sin_f32_e32 v211, v194
	v_cos_f32_e32 v203, v194
	s_waitcnt lgkmcnt(0)
	v_mul_f32_e32 v204, v204, v184
	v_mul_f32_e32 v196, v196, v48
	v_mul_f32_e32 v204, v204, v192
	v_add_f32_e32 v196, v196, v204
	v_cndmask_b32_e64 v56, v48, v196, s[68:69]
	v_mul_f32_e32 v205, v205, v185
	v_mul_f32_e32 v197, v197, v49
	v_mul_f32_e32 v205, v205, v192
	v_add_f32_e32 v197, v197, v205
	v_cndmask_b32_e64 v57, v49, v197, s[68:69]
	v_mul_f32_e32 v206, v206, v186
	v_mul_f32_e32 v198, v198, v50
	v_mul_f32_e32 v206, v206, v192
	v_add_f32_e32 v198, v198, v206
	v_cndmask_b32_e64 v58, v50, v198, s[68:69]
	v_mul_f32_e32 v207, v207, v187
	v_mul_f32_e32 v199, v199, v51
	v_mul_f32_e32 v207, v207, v192
	v_add_f32_e32 v199, v199, v207
	v_cndmask_b32_e64 v59, v51, v199, s[68:69]
	v_mul_f32_e32 v208, v208, v188
	v_mul_f32_e32 v200, v200, v52
	v_mul_f32_e32 v208, v208, v192
	v_add_f32_e32 v200, v200, v208
	v_cndmask_b32_e64 v60, v52, v200, s[68:69]
	v_mul_f32_e32 v209, v209, v189
	v_mul_f32_e32 v201, v201, v53
	v_mul_f32_e32 v209, v209, v192
	v_add_f32_e32 v201, v201, v209
	v_cndmask_b32_e64 v61, v53, v201, s[68:69]
	v_mul_f32_e32 v210, v210, v190
	v_mul_f32_e32 v202, v202, v54
	v_mul_f32_e32 v210, v210, v192
	v_add_f32_e32 v202, v202, v210
	v_cndmask_b32_e64 v62, v54, v202, s[68:69]
	v_mul_f32_e32 v211, v211, v191
	v_mul_f32_e32 v203, v203, v55
	v_mul_f32_e32 v211, v211, v192
	v_add_f32_e32 v203, v203, v211
	v_cndmask_b32_e64 v63, v55, v203, s[68:69]
	s_branch .LBB0_634

.LBB0_634:
	v_mov_b64_e32 v[52:53], s[78:79]
	v_mad_i64_i32 v[52:53], s[28:29], v66, s26, v[52:53]
	v_cvt_pk_bf16_f32 v48, v56, v57
	v_cvt_pk_bf16_f32 v49, v58, v59
	v_cvt_pk_bf16_f32 v50, v60, v61
	v_cvt_pk_bf16_f32 v51, v62, v63
	v_lshl_add_u64 v[52:53], v[64:65], 1, v[52:53]
	s_and_b64 vcc, exec, s[38:39]
	v_or_b32_e32 v56, 32, v181
	global_store_dwordx4 v[52:53], v[48:51], off offset:256 nt
	s_cbranch_vccnz .LBB0_684
	v_add_u32_e32 v182, 32, v181
	v_xor_b32_e32 v183, 16, v180
	v_and_b32_e32 v182, 0xfff, v182
	v_lshlrev_b32_e32 v183, 2, v183
	v_cvt_f32_u32_e32 v182, v182
	v_cmp_eq_u32_e64 s[60:61], 0, v171
	v_cmp_gt_u32_e64 s[68:69], 2, v171
	ds_bpermute_b32 v184, v183, v40
	ds_bpermute_b32 v185, v183, v41
	ds_bpermute_b32 v186, v183, v42
	ds_bpermute_b32 v187, v183, v43
	ds_bpermute_b32 v188, v183, v44
	ds_bpermute_b32 v189, v183, v45
	ds_bpermute_b32 v190, v183, v46
	ds_bpermute_b32 v191, v183, v47
	v_mov_b32_e32 v192, 1.0
	v_cndmask_b32_e64 v192, v192, -1.0, s[60:61]
	v_mul_f32_e32 v194, 0.15915494, v182
	v_rndne_f32_e32 v194, v194
	v_fma_f32 v194, v182, 0.15915494, -v194
	v_mul_f32_e32 v194, 0x40c90fdb, v194
	v_mul_f32_e32 v194, 0.15915494, v194
	v_sin_f32_e32 v204, v194
	v_cos_f32_e32 v196, v194
	v_mul_f32_e32 v193, 0x3e4693af, v182
	v_mul_f32_e32 v194, 0.15915494, v193
	v_rndne_f32_e32 v194, v194
	v_fma_f32 v194, v193, 0.15915494, -v194
	v_mul_f32_e32 v194, 0x40c90fdb, v194
	v_mul_f32_e32 v194, 0.15915494, v194
	v_sin_f32_e32 v205, v194
	v_cos_f32_e32 v197, v194
	v_mul_f32_e32 v193, 0x3d1a08c8, v182
	v_mul_f32_e32 v194, 0.15915494, v193
	v_rndne_f32_e32 v194, v194
	v_fma_f32 v194, v193, 0.15915494, -v194
	v_mul_f32_e32 v194, 0x40c90fdb, v194
	v_mul_f32_e32 v194, 0.15915494, v194
	v_sin_f32_e32 v206, v194
	v_cos_f32_e32 v198, v194
	v_mul_f32_e32 v193, 0x3beef74e, v182
	v_mul_f32_e32 v194, 0.15915494, v193
	v_rndne_f32_e32 v194, v194
	v_fma_f32 v194, v193, 0.15915494, -v194
	v_mul_f32_e32 v194, 0x40c90fdb, v194
	v_mul_f32_e32 v194, 0.15915494, v194
	v_sin_f32_e32 v207, v194
	v_cos_f32_e32 v199, v194
	v_mul_f32_e32 v193, 0x3ab95d22, v182
	v_mul_f32_e32 v194, 0.15915494, v193
	v_rndne_f32_e32 v194, v194
	v_fma_f32 v194, v193, 0.15915494, -v194
	v_mul_f32_e32 v194, 0x40c90fdb, v194
	v_mul_f32_e32 v194, 0.15915494, v194
	v_sin_f32_e32 v208, v194
	v_cos_f32_e32 v200, v194
	v_mul_f32_e32 v193, 0x398fc8f8, v182
	v_mul_f32_e32 v194, 0.15915494, v193
	v_rndne_f32_e32 v194, v194
	v_fma_f32 v194, v193, 0.15915494, -v194
	v_mul_f32_e32 v194, 0x40c90fdb, v194
	v_mul_f32_e32 v194, 0.15915494, v194
	v_sin_f32_e32 v209, v194
	v_cos_f32_e32 v201, v194
	v_mul_f32_e32 v193, 0x385f10c4, v182
	v_mul_f32_e32 v194, 0.15915494, v193
	v_rndne_f32_e32 v194, v194
	v_fma_f32 v194, v193, 0.15915494, -v194
	v_mul_f32_e32 v194, 0x40c90fdb, v194
	v_mul_f32_e32 v194, 0.15915494, v194
	v_sin_f32_e32 v210, v194
	v_cos_f32_e32 v202, v194
	v_mul_f32_e32 v193, 0x372d07a7, v182
	v_mul_f32_e32 v194, 0.15915494, v193
	v_rndne_f32_e32 v194, v194
	v_fma_f32 v194, v193, 0.15915494, -v194
	v_mul_f32_e32 v194, 0x40c90fdb, v194
	v_mul_f32_e32 v194, 0.15915494, v194
	v_sin_f32_e32 v211, v194
	v_cos_f32_e32 v203, v194
	s_waitcnt lgkmcnt(0)
	v_mul_f32_e32 v204, v204, v184
	v_mul_f32_e32 v196, v196, v40
	v_mul_f32_e32 v204, v204, v192
	v_add_f32_e32 v196, v196, v204
	v_cndmask_b32_e64 v48, v40, v196, s[68:69]
	v_mul_f32_e32 v205, v205, v185
	v_mul_f32_e32 v197, v197, v41
	v_mul_f32_e32 v205, v205, v192
	v_add_f32_e32 v197, v197, v205
	v_cndmask_b32_e64 v49, v41, v197, s[68:69]
	v_mul_f32_e32 v206, v206, v186
	v_mul_f32_e32 v198, v198, v42
	v_mul_f32_e32 v206, v206, v192
	v_add_f32_e32 v198, v198, v206
	v_cndmask_b32_e64 v50, v42, v198, s[68:69]
	v_mul_f32_e32 v207, v207, v187
	v_mul_f32_e32 v199, v199, v43
	v_mul_f32_e32 v207, v207, v192
	v_add_f32_e32 v199, v199, v207
	v_cndmask_b32_e64 v51, v43, v199, s[68:69]
	v_mul_f32_e32 v208, v208, v188
	v_mul_f32_e32 v200, v200, v44
	v_mul_f32_e32 v208, v208, v192
	v_add_f32_e32 v200, v200, v208
	v_cndmask_b32_e64 v52, v44, v200, s[68:69]
	v_mul_f32_e32 v209, v209, v189
	v_mul_f32_e32 v201, v201, v45
	v_mul_f32_e32 v209, v209, v192
	v_add_f32_e32 v201, v201, v209
	v_cndmask_b32_e64 v53, v45, v201, s[68:69]
	v_mul_f32_e32 v210, v210, v190
	v_mul_f32_e32 v202, v202, v46
	v_mul_f32_e32 v210, v210, v192
	v_add_f32_e32 v202, v202, v210
	v_cndmask_b32_e64 v54, v46, v202, s[68:69]
	v_mul_f32_e32 v211, v211, v191
	v_mul_f32_e32 v203, v203, v47
	v_mul_f32_e32 v211, v211, v192
	v_add_f32_e32 v203, v203, v211
	v_cndmask_b32_e64 v55, v47, v203, s[68:69]
	s_branch .LBB0_685

.LBB0_685:
	v_mov_b64_e32 v[44:45], s[78:79]
	v_mad_i64_i32 v[44:45], s[28:29], v56, s26, v[44:45]
	v_cvt_pk_bf16_f32 v40, v48, v49
	v_cvt_pk_bf16_f32 v41, v50, v51
	v_cvt_pk_bf16_f32 v42, v52, v53
	v_cvt_pk_bf16_f32 v43, v54, v55
	v_lshl_add_u64 v[44:45], v[64:65], 1, v[44:45]
	s_and_b64 vcc, exec, s[38:39]
	v_or_b32_e32 v48, 48, v181
	global_store_dwordx4 v[44:45], v[40:43], off offset:256 nt
	s_cbranch_vccnz .LBB0_735
	v_add_u32_e32 v182, 48, v181
	v_xor_b32_e32 v183, 16, v180
	v_and_b32_e32 v182, 0xfff, v182
	v_lshlrev_b32_e32 v183, 2, v183
	v_cvt_f32_u32_e32 v182, v182
	v_cmp_eq_u32_e64 s[60:61], 0, v171
	v_cmp_gt_u32_e64 s[68:69], 2, v171
	ds_bpermute_b32 v184, v183, v32
	ds_bpermute_b32 v185, v183, v33
	ds_bpermute_b32 v186, v183, v34
	ds_bpermute_b32 v187, v183, v35
	ds_bpermute_b32 v188, v183, v36
	ds_bpermute_b32 v189, v183, v37
	ds_bpermute_b32 v190, v183, v38
	ds_bpermute_b32 v191, v183, v39
	v_mov_b32_e32 v192, 1.0
	v_cndmask_b32_e64 v192, v192, -1.0, s[60:61]
	v_mul_f32_e32 v194, 0.15915494, v182
	v_rndne_f32_e32 v194, v194
	v_fma_f32 v194, v182, 0.15915494, -v194
	v_mul_f32_e32 v194, 0x40c90fdb, v194
	v_mul_f32_e32 v194, 0.15915494, v194
	v_sin_f32_e32 v204, v194
	v_cos_f32_e32 v196, v194
	v_mul_f32_e32 v193, 0x3e4693af, v182
	v_mul_f32_e32 v194, 0.15915494, v193
	v_rndne_f32_e32 v194, v194
	v_fma_f32 v194, v193, 0.15915494, -v194
	v_mul_f32_e32 v194, 0x40c90fdb, v194
	v_mul_f32_e32 v194, 0.15915494, v194
	v_sin_f32_e32 v205, v194
	v_cos_f32_e32 v197, v194
	v_mul_f32_e32 v193, 0x3d1a08c8, v182
	v_mul_f32_e32 v194, 0.15915494, v193
	v_rndne_f32_e32 v194, v194
	v_fma_f32 v194, v193, 0.15915494, -v194
	v_mul_f32_e32 v194, 0x40c90fdb, v194
	v_mul_f32_e32 v194, 0.15915494, v194
	v_sin_f32_e32 v206, v194
	v_cos_f32_e32 v198, v194
	v_mul_f32_e32 v193, 0x3beef74e, v182
	v_mul_f32_e32 v194, 0.15915494, v193
	v_rndne_f32_e32 v194, v194
	v_fma_f32 v194, v193, 0.15915494, -v194
	v_mul_f32_e32 v194, 0x40c90fdb, v194
	v_mul_f32_e32 v194, 0.15915494, v194
	v_sin_f32_e32 v207, v194
	v_cos_f32_e32 v199, v194
	v_mul_f32_e32 v193, 0x3ab95d22, v182
	v_mul_f32_e32 v194, 0.15915494, v193
	v_rndne_f32_e32 v194, v194
	v_fma_f32 v194, v193, 0.15915494, -v194
	v_mul_f32_e32 v194, 0x40c90fdb, v194
	v_mul_f32_e32 v194, 0.15915494, v194
	v_sin_f32_e32 v208, v194
	v_cos_f32_e32 v200, v194
	v_mul_f32_e32 v193, 0x398fc8f8, v182
	v_mul_f32_e32 v194, 0.15915494, v193
	v_rndne_f32_e32 v194, v194
	v_fma_f32 v194, v193, 0.15915494, -v194
	v_mul_f32_e32 v194, 0x40c90fdb, v194
	v_mul_f32_e32 v194, 0.15915494, v194
	v_sin_f32_e32 v209, v194
	v_cos_f32_e32 v201, v194
	v_mul_f32_e32 v193, 0x385f10c4, v182
	v_mul_f32_e32 v194, 0.15915494, v193
	v_rndne_f32_e32 v194, v194
	v_fma_f32 v194, v193, 0.15915494, -v194
	v_mul_f32_e32 v194, 0x40c90fdb, v194
	v_mul_f32_e32 v194, 0.15915494, v194
	v_sin_f32_e32 v210, v194
	v_cos_f32_e32 v202, v194
	v_mul_f32_e32 v193, 0x372d07a7, v182
	v_mul_f32_e32 v194, 0.15915494, v193
	v_rndne_f32_e32 v194, v194
	v_fma_f32 v194, v193, 0.15915494, -v194
	v_mul_f32_e32 v194, 0x40c90fdb, v194
	v_mul_f32_e32 v194, 0.15915494, v194
	v_sin_f32_e32 v211, v194
	v_cos_f32_e32 v203, v194
	s_waitcnt lgkmcnt(0)
	v_mul_f32_e32 v204, v204, v184
	v_mul_f32_e32 v196, v196, v32
	v_mul_f32_e32 v204, v204, v192
	v_add_f32_e32 v196, v196, v204
	v_cndmask_b32_e64 v40, v32, v196, s[68:69]
	v_mul_f32_e32 v205, v205, v185
	v_mul_f32_e32 v197, v197, v33
	v_mul_f32_e32 v205, v205, v192
	v_add_f32_e32 v197, v197, v205
	v_cndmask_b32_e64 v41, v33, v197, s[68:69]
	v_mul_f32_e32 v206, v206, v186
	v_mul_f32_e32 v198, v198, v34
	v_mul_f32_e32 v206, v206, v192
	v_add_f32_e32 v198, v198, v206
	v_cndmask_b32_e64 v42, v34, v198, s[68:69]
	v_mul_f32_e32 v207, v207, v187
	v_mul_f32_e32 v199, v199, v35
	v_mul_f32_e32 v207, v207, v192
	v_add_f32_e32 v199, v199, v207
	v_cndmask_b32_e64 v43, v35, v199, s[68:69]
	v_mul_f32_e32 v208, v208, v188
	v_mul_f32_e32 v200, v200, v36
	v_mul_f32_e32 v208, v208, v192
	v_add_f32_e32 v200, v200, v208
	v_cndmask_b32_e64 v44, v36, v200, s[68:69]
	v_mul_f32_e32 v209, v209, v189
	v_mul_f32_e32 v201, v201, v37
	v_mul_f32_e32 v209, v209, v192
	v_add_f32_e32 v201, v201, v209
	v_cndmask_b32_e64 v45, v37, v201, s[68:69]
	v_mul_f32_e32 v210, v210, v190
	v_mul_f32_e32 v202, v202, v38
	v_mul_f32_e32 v210, v210, v192
	v_add_f32_e32 v202, v202, v210
	v_cndmask_b32_e64 v46, v38, v202, s[68:69]
	v_mul_f32_e32 v211, v211, v191
	v_mul_f32_e32 v203, v203, v39
	v_mul_f32_e32 v211, v211, v192
	v_add_f32_e32 v203, v203, v211
	v_cndmask_b32_e64 v47, v39, v203, s[68:69]
	s_branch .LBB0_736

.LBB0_736:
	v_mov_b64_e32 v[36:37], s[78:79]
	v_mad_i64_i32 v[36:37], s[28:29], v48, s26, v[36:37]
	v_cvt_pk_bf16_f32 v32, v40, v41
	v_cvt_pk_bf16_f32 v33, v42, v43
	v_cvt_pk_bf16_f32 v34, v44, v45
	v_cvt_pk_bf16_f32 v35, v46, v47
	v_lshl_add_u64 v[36:37], v[64:65], 1, v[36:37]
	s_and_b64 vcc, exec, s[38:39]
	v_add_u32_e32 v40, 0x80, v181
	global_store_dwordx4 v[36:37], v[32:35], off offset:256 nt
	s_cbranch_vccnz .LBB0_786
	v_add_u32_e32 v182, 128, v181
	v_xor_b32_e32 v183, 16, v180
	v_and_b32_e32 v182, 0xfff, v182
	v_lshlrev_b32_e32 v183, 2, v183
	v_cvt_f32_u32_e32 v182, v182
	v_cmp_eq_u32_e64 s[60:61], 0, v171
	v_cmp_gt_u32_e64 s[68:69], 2, v171
	ds_bpermute_b32 v184, v183, v24
	ds_bpermute_b32 v185, v183, v25
	ds_bpermute_b32 v186, v183, v26
	ds_bpermute_b32 v187, v183, v27
	ds_bpermute_b32 v188, v183, v28
	ds_bpermute_b32 v189, v183, v29
	ds_bpermute_b32 v190, v183, v30
	ds_bpermute_b32 v191, v183, v31
	v_mov_b32_e32 v192, 1.0
	v_cndmask_b32_e64 v192, v192, -1.0, s[60:61]
	v_mul_f32_e32 v194, 0.15915494, v182
	v_rndne_f32_e32 v194, v194
	v_fma_f32 v194, v182, 0.15915494, -v194
	v_mul_f32_e32 v194, 0x40c90fdb, v194
	v_mul_f32_e32 v194, 0.15915494, v194
	v_sin_f32_e32 v204, v194
	v_cos_f32_e32 v196, v194
	v_mul_f32_e32 v193, 0x3e4693af, v182
	v_mul_f32_e32 v194, 0.15915494, v193
	v_rndne_f32_e32 v194, v194
	v_fma_f32 v194, v193, 0.15915494, -v194
	v_mul_f32_e32 v194, 0x40c90fdb, v194
	v_mul_f32_e32 v194, 0.15915494, v194
	v_sin_f32_e32 v205, v194
	v_cos_f32_e32 v197, v194
	v_mul_f32_e32 v193, 0x3d1a08c8, v182
	v_mul_f32_e32 v194, 0.15915494, v193
	v_rndne_f32_e32 v194, v194
	v_fma_f32 v194, v193, 0.15915494, -v194
	v_mul_f32_e32 v194, 0x40c90fdb, v194
	v_mul_f32_e32 v194, 0.15915494, v194
	v_sin_f32_e32 v206, v194
	v_cos_f32_e32 v198, v194
	v_mul_f32_e32 v193, 0x3beef74e, v182
	v_mul_f32_e32 v194, 0.15915494, v193
	v_rndne_f32_e32 v194, v194
	v_fma_f32 v194, v193, 0.15915494, -v194
	v_mul_f32_e32 v194, 0x40c90fdb, v194
	v_mul_f32_e32 v194, 0.15915494, v194
	v_sin_f32_e32 v207, v194
	v_cos_f32_e32 v199, v194
	v_mul_f32_e32 v193, 0x3ab95d22, v182
	v_mul_f32_e32 v194, 0.15915494, v193
	v_rndne_f32_e32 v194, v194
	v_fma_f32 v194, v193, 0.15915494, -v194
	v_mul_f32_e32 v194, 0x40c90fdb, v194
	v_mul_f32_e32 v194, 0.15915494, v194
	v_sin_f32_e32 v208, v194
	v_cos_f32_e32 v200, v194
	v_mul_f32_e32 v193, 0x398fc8f8, v182
	v_mul_f32_e32 v194, 0.15915494, v193
	v_rndne_f32_e32 v194, v194
	v_fma_f32 v194, v193, 0.15915494, -v194
	v_mul_f32_e32 v194, 0x40c90fdb, v194
	v_mul_f32_e32 v194, 0.15915494, v194
	v_sin_f32_e32 v209, v194
	v_cos_f32_e32 v201, v194
	v_mul_f32_e32 v193, 0x385f10c4, v182
	v_mul_f32_e32 v194, 0.15915494, v193
	v_rndne_f32_e32 v194, v194
	v_fma_f32 v194, v193, 0.15915494, -v194
	v_mul_f32_e32 v194, 0x40c90fdb, v194
	v_mul_f32_e32 v194, 0.15915494, v194
	v_sin_f32_e32 v210, v194
	v_cos_f32_e32 v202, v194
	v_mul_f32_e32 v193, 0x372d07a7, v182
	v_mul_f32_e32 v194, 0.15915494, v193
	v_rndne_f32_e32 v194, v194
	v_fma_f32 v194, v193, 0.15915494, -v194
	v_mul_f32_e32 v194, 0x40c90fdb, v194
	v_mul_f32_e32 v194, 0.15915494, v194
	v_sin_f32_e32 v211, v194
	v_cos_f32_e32 v203, v194
	s_waitcnt lgkmcnt(0)
	v_mul_f32_e32 v204, v204, v184
	v_mul_f32_e32 v196, v196, v24
	v_mul_f32_e32 v204, v204, v192
	v_add_f32_e32 v196, v196, v204
	v_cndmask_b32_e64 v32, v24, v196, s[68:69]
	v_mul_f32_e32 v205, v205, v185
	v_mul_f32_e32 v197, v197, v25
	v_mul_f32_e32 v205, v205, v192
	v_add_f32_e32 v197, v197, v205
	v_cndmask_b32_e64 v33, v25, v197, s[68:69]
	v_mul_f32_e32 v206, v206, v186
	v_mul_f32_e32 v198, v198, v26
	v_mul_f32_e32 v206, v206, v192
	v_add_f32_e32 v198, v198, v206
	v_cndmask_b32_e64 v34, v26, v198, s[68:69]
	v_mul_f32_e32 v207, v207, v187
	v_mul_f32_e32 v199, v199, v27
	v_mul_f32_e32 v207, v207, v192
	v_add_f32_e32 v199, v199, v207
	v_cndmask_b32_e64 v35, v27, v199, s[68:69]
	v_mul_f32_e32 v208, v208, v188
	v_mul_f32_e32 v200, v200, v28
	v_mul_f32_e32 v208, v208, v192
	v_add_f32_e32 v200, v200, v208
	v_cndmask_b32_e64 v36, v28, v200, s[68:69]
	v_mul_f32_e32 v209, v209, v189
	v_mul_f32_e32 v201, v201, v29
	v_mul_f32_e32 v209, v209, v192
	v_add_f32_e32 v201, v201, v209
	v_cndmask_b32_e64 v37, v29, v201, s[68:69]
	v_mul_f32_e32 v210, v210, v190
	v_mul_f32_e32 v202, v202, v30
	v_mul_f32_e32 v210, v210, v192
	v_add_f32_e32 v202, v202, v210
	v_cndmask_b32_e64 v38, v30, v202, s[68:69]
	v_mul_f32_e32 v211, v211, v191
	v_mul_f32_e32 v203, v203, v31
	v_mul_f32_e32 v211, v211, v192
	v_add_f32_e32 v203, v203, v211
	v_cndmask_b32_e64 v39, v31, v203, s[68:69]
	s_branch .LBB0_787

.LBB0_787:
	v_mov_b64_e32 v[28:29], s[78:79]
	v_mad_i64_i32 v[28:29], s[28:29], v40, s26, v[28:29]
	v_cvt_pk_bf16_f32 v24, v32, v33
	v_cvt_pk_bf16_f32 v25, v34, v35
	v_cvt_pk_bf16_f32 v26, v36, v37
	v_cvt_pk_bf16_f32 v27, v38, v39
	v_lshl_add_u64 v[28:29], v[64:65], 1, v[28:29]
	s_and_b64 vcc, exec, s[38:39]
	v_add_u32_e32 v32, 0x90, v181
	global_store_dwordx4 v[28:29], v[24:27], off offset:256 nt
	s_cbranch_vccnz .LBB0_837
	v_add_u32_e32 v182, 144, v181
	v_xor_b32_e32 v183, 16, v180
	v_and_b32_e32 v182, 0xfff, v182
	v_lshlrev_b32_e32 v183, 2, v183
	v_cvt_f32_u32_e32 v182, v182
	v_cmp_eq_u32_e64 s[60:61], 0, v171
	v_cmp_gt_u32_e64 s[68:69], 2, v171
	ds_bpermute_b32 v184, v183, v16
	ds_bpermute_b32 v185, v183, v17
	ds_bpermute_b32 v186, v183, v18
	ds_bpermute_b32 v187, v183, v19
	ds_bpermute_b32 v188, v183, v20
	ds_bpermute_b32 v189, v183, v21
	ds_bpermute_b32 v190, v183, v22
	ds_bpermute_b32 v191, v183, v23
	v_mov_b32_e32 v192, 1.0
	v_cndmask_b32_e64 v192, v192, -1.0, s[60:61]
	v_mul_f32_e32 v194, 0.15915494, v182
	v_rndne_f32_e32 v194, v194
	v_fma_f32 v194, v182, 0.15915494, -v194
	v_mul_f32_e32 v194, 0x40c90fdb, v194
	v_mul_f32_e32 v194, 0.15915494, v194
	v_sin_f32_e32 v204, v194
	v_cos_f32_e32 v196, v194
	v_mul_f32_e32 v193, 0x3e4693af, v182
	v_mul_f32_e32 v194, 0.15915494, v193
	v_rndne_f32_e32 v194, v194
	v_fma_f32 v194, v193, 0.15915494, -v194
	v_mul_f32_e32 v194, 0x40c90fdb, v194
	v_mul_f32_e32 v194, 0.15915494, v194
	v_sin_f32_e32 v205, v194
	v_cos_f32_e32 v197, v194
	v_mul_f32_e32 v193, 0x3d1a08c8, v182
	v_mul_f32_e32 v194, 0.15915494, v193
	v_rndne_f32_e32 v194, v194
	v_fma_f32 v194, v193, 0.15915494, -v194
	v_mul_f32_e32 v194, 0x40c90fdb, v194
	v_mul_f32_e32 v194, 0.15915494, v194
	v_sin_f32_e32 v206, v194
	v_cos_f32_e32 v198, v194
	v_mul_f32_e32 v193, 0x3beef74e, v182
	v_mul_f32_e32 v194, 0.15915494, v193
	v_rndne_f32_e32 v194, v194
	v_fma_f32 v194, v193, 0.15915494, -v194
	v_mul_f32_e32 v194, 0x40c90fdb, v194
	v_mul_f32_e32 v194, 0.15915494, v194
	v_sin_f32_e32 v207, v194
	v_cos_f32_e32 v199, v194
	v_mul_f32_e32 v193, 0x3ab95d22, v182
	v_mul_f32_e32 v194, 0.15915494, v193
	v_rndne_f32_e32 v194, v194
	v_fma_f32 v194, v193, 0.15915494, -v194
	v_mul_f32_e32 v194, 0x40c90fdb, v194
	v_mul_f32_e32 v194, 0.15915494, v194
	v_sin_f32_e32 v208, v194
	v_cos_f32_e32 v200, v194
	v_mul_f32_e32 v193, 0x398fc8f8, v182
	v_mul_f32_e32 v194, 0.15915494, v193
	v_rndne_f32_e32 v194, v194
	v_fma_f32 v194, v193, 0.15915494, -v194
	v_mul_f32_e32 v194, 0x40c90fdb, v194
	v_mul_f32_e32 v194, 0.15915494, v194
	v_sin_f32_e32 v209, v194
	v_cos_f32_e32 v201, v194
	v_mul_f32_e32 v193, 0x385f10c4, v182
	v_mul_f32_e32 v194, 0.15915494, v193
	v_rndne_f32_e32 v194, v194
	v_fma_f32 v194, v193, 0.15915494, -v194
	v_mul_f32_e32 v194, 0x40c90fdb, v194
	v_mul_f32_e32 v194, 0.15915494, v194
	v_sin_f32_e32 v210, v194
	v_cos_f32_e32 v202, v194
	v_mul_f32_e32 v193, 0x372d07a7, v182
	v_mul_f32_e32 v194, 0.15915494, v193
	v_rndne_f32_e32 v194, v194
	v_fma_f32 v194, v193, 0.15915494, -v194
	v_mul_f32_e32 v194, 0x40c90fdb, v194
	v_mul_f32_e32 v194, 0.15915494, v194
	v_sin_f32_e32 v211, v194
	v_cos_f32_e32 v203, v194
	s_waitcnt lgkmcnt(0)
	v_mul_f32_e32 v204, v204, v184
	v_mul_f32_e32 v196, v196, v16
	v_mul_f32_e32 v204, v204, v192
	v_add_f32_e32 v196, v196, v204
	v_cndmask_b32_e64 v24, v16, v196, s[68:69]
	v_mul_f32_e32 v205, v205, v185
	v_mul_f32_e32 v197, v197, v17
	v_mul_f32_e32 v205, v205, v192
	v_add_f32_e32 v197, v197, v205
	v_cndmask_b32_e64 v25, v17, v197, s[68:69]
	v_mul_f32_e32 v206, v206, v186
	v_mul_f32_e32 v198, v198, v18
	v_mul_f32_e32 v206, v206, v192
	v_add_f32_e32 v198, v198, v206
	v_cndmask_b32_e64 v26, v18, v198, s[68:69]
	v_mul_f32_e32 v207, v207, v187
	v_mul_f32_e32 v199, v199, v19
	v_mul_f32_e32 v207, v207, v192
	v_add_f32_e32 v199, v199, v207
	v_cndmask_b32_e64 v27, v19, v199, s[68:69]
	v_mul_f32_e32 v208, v208, v188
	v_mul_f32_e32 v200, v200, v20
	v_mul_f32_e32 v208, v208, v192
	v_add_f32_e32 v200, v200, v208
	v_cndmask_b32_e64 v28, v20, v200, s[68:69]
	v_mul_f32_e32 v209, v209, v189
	v_mul_f32_e32 v201, v201, v21
	v_mul_f32_e32 v209, v209, v192
	v_add_f32_e32 v201, v201, v209
	v_cndmask_b32_e64 v29, v21, v201, s[68:69]
	v_mul_f32_e32 v210, v210, v190
	v_mul_f32_e32 v202, v202, v22
	v_mul_f32_e32 v210, v210, v192
	v_add_f32_e32 v202, v202, v210
	v_cndmask_b32_e64 v30, v22, v202, s[68:69]
	v_mul_f32_e32 v211, v211, v191
	v_mul_f32_e32 v203, v203, v23
	v_mul_f32_e32 v211, v211, v192
	v_add_f32_e32 v203, v203, v211
	v_cndmask_b32_e64 v31, v23, v203, s[68:69]
	s_branch .LBB0_838

.LBB0_838:
	v_mov_b64_e32 v[20:21], s[78:79]
	v_mad_i64_i32 v[20:21], s[28:29], v32, s26, v[20:21]
	v_cvt_pk_bf16_f32 v16, v24, v25
	v_cvt_pk_bf16_f32 v17, v26, v27
	v_cvt_pk_bf16_f32 v18, v28, v29
	v_cvt_pk_bf16_f32 v19, v30, v31
	v_lshl_add_u64 v[20:21], v[64:65], 1, v[20:21]
	s_and_b64 vcc, exec, s[38:39]
	v_add_u32_e32 v24, 0xa0, v181
	global_store_dwordx4 v[20:21], v[16:19], off offset:256 nt
	s_cbranch_vccnz .LBB0_888
	v_add_u32_e32 v182, 160, v181
	v_xor_b32_e32 v183, 16, v180
	v_and_b32_e32 v182, 0xfff, v182
	v_lshlrev_b32_e32 v183, 2, v183
	v_cvt_f32_u32_e32 v182, v182
	v_cmp_eq_u32_e64 s[60:61], 0, v171
	v_cmp_gt_u32_e64 s[68:69], 2, v171
	ds_bpermute_b32 v184, v183, v8
	ds_bpermute_b32 v185, v183, v9
	ds_bpermute_b32 v186, v183, v10
	ds_bpermute_b32 v187, v183, v11
	ds_bpermute_b32 v188, v183, v12
	ds_bpermute_b32 v189, v183, v13
	ds_bpermute_b32 v190, v183, v14
	ds_bpermute_b32 v191, v183, v15
	v_mov_b32_e32 v192, 1.0
	v_cndmask_b32_e64 v192, v192, -1.0, s[60:61]
	v_mul_f32_e32 v194, 0.15915494, v182
	v_rndne_f32_e32 v194, v194
	v_fma_f32 v194, v182, 0.15915494, -v194
	v_mul_f32_e32 v194, 0x40c90fdb, v194
	v_mul_f32_e32 v194, 0.15915494, v194
	v_sin_f32_e32 v204, v194
	v_cos_f32_e32 v196, v194
	v_mul_f32_e32 v193, 0x3e4693af, v182
	v_mul_f32_e32 v194, 0.15915494, v193
	v_rndne_f32_e32 v194, v194
	v_fma_f32 v194, v193, 0.15915494, -v194
	v_mul_f32_e32 v194, 0x40c90fdb, v194
	v_mul_f32_e32 v194, 0.15915494, v194
	v_sin_f32_e32 v205, v194
	v_cos_f32_e32 v197, v194
	v_mul_f32_e32 v193, 0x3d1a08c8, v182
	v_mul_f32_e32 v194, 0.15915494, v193
	v_rndne_f32_e32 v194, v194
	v_fma_f32 v194, v193, 0.15915494, -v194
	v_mul_f32_e32 v194, 0x40c90fdb, v194
	v_mul_f32_e32 v194, 0.15915494, v194
	v_sin_f32_e32 v206, v194
	v_cos_f32_e32 v198, v194
	v_mul_f32_e32 v193, 0x3beef74e, v182
	v_mul_f32_e32 v194, 0.15915494, v193
	v_rndne_f32_e32 v194, v194
	v_fma_f32 v194, v193, 0.15915494, -v194
	v_mul_f32_e32 v194, 0x40c90fdb, v194
	v_mul_f32_e32 v194, 0.15915494, v194
	v_sin_f32_e32 v207, v194
	v_cos_f32_e32 v199, v194
	v_mul_f32_e32 v193, 0x3ab95d22, v182
	v_mul_f32_e32 v194, 0.15915494, v193
	v_rndne_f32_e32 v194, v194
	v_fma_f32 v194, v193, 0.15915494, -v194
	v_mul_f32_e32 v194, 0x40c90fdb, v194
	v_mul_f32_e32 v194, 0.15915494, v194
	v_sin_f32_e32 v208, v194
	v_cos_f32_e32 v200, v194
	v_mul_f32_e32 v193, 0x398fc8f8, v182
	v_mul_f32_e32 v194, 0.15915494, v193
	v_rndne_f32_e32 v194, v194
	v_fma_f32 v194, v193, 0.15915494, -v194
	v_mul_f32_e32 v194, 0x40c90fdb, v194
	v_mul_f32_e32 v194, 0.15915494, v194
	v_sin_f32_e32 v209, v194
	v_cos_f32_e32 v201, v194
	v_mul_f32_e32 v193, 0x385f10c4, v182
	v_mul_f32_e32 v194, 0.15915494, v193
	v_rndne_f32_e32 v194, v194
	v_fma_f32 v194, v193, 0.15915494, -v194
	v_mul_f32_e32 v194, 0x40c90fdb, v194
	v_mul_f32_e32 v194, 0.15915494, v194
	v_sin_f32_e32 v210, v194
	v_cos_f32_e32 v202, v194
	v_mul_f32_e32 v193, 0x372d07a7, v182
	v_mul_f32_e32 v194, 0.15915494, v193
	v_rndne_f32_e32 v194, v194
	v_fma_f32 v194, v193, 0.15915494, -v194
	v_mul_f32_e32 v194, 0x40c90fdb, v194
	v_mul_f32_e32 v194, 0.15915494, v194
	v_sin_f32_e32 v211, v194
	v_cos_f32_e32 v203, v194
	s_waitcnt lgkmcnt(0)
	v_mul_f32_e32 v204, v204, v184
	v_mul_f32_e32 v196, v196, v8
	v_mul_f32_e32 v204, v204, v192
	v_add_f32_e32 v196, v196, v204
	v_cndmask_b32_e64 v16, v8, v196, s[68:69]
	v_mul_f32_e32 v205, v205, v185
	v_mul_f32_e32 v197, v197, v9
	v_mul_f32_e32 v205, v205, v192
	v_add_f32_e32 v197, v197, v205
	v_cndmask_b32_e64 v17, v9, v197, s[68:69]
	v_mul_f32_e32 v206, v206, v186
	v_mul_f32_e32 v198, v198, v10
	v_mul_f32_e32 v206, v206, v192
	v_add_f32_e32 v198, v198, v206
	v_cndmask_b32_e64 v18, v10, v198, s[68:69]
	v_mul_f32_e32 v207, v207, v187
	v_mul_f32_e32 v199, v199, v11
	v_mul_f32_e32 v207, v207, v192
	v_add_f32_e32 v199, v199, v207
	v_cndmask_b32_e64 v19, v11, v199, s[68:69]
	v_mul_f32_e32 v208, v208, v188
	v_mul_f32_e32 v200, v200, v12
	v_mul_f32_e32 v208, v208, v192
	v_add_f32_e32 v200, v200, v208
	v_cndmask_b32_e64 v20, v12, v200, s[68:69]
	v_mul_f32_e32 v209, v209, v189
	v_mul_f32_e32 v201, v201, v13
	v_mul_f32_e32 v209, v209, v192
	v_add_f32_e32 v201, v201, v209
	v_cndmask_b32_e64 v21, v13, v201, s[68:69]
	v_mul_f32_e32 v210, v210, v190
	v_mul_f32_e32 v202, v202, v14
	v_mul_f32_e32 v210, v210, v192
	v_add_f32_e32 v202, v202, v210
	v_cndmask_b32_e64 v22, v14, v202, s[68:69]
	v_mul_f32_e32 v211, v211, v191
	v_mul_f32_e32 v203, v203, v15
	v_mul_f32_e32 v211, v211, v192
	v_add_f32_e32 v203, v203, v211
	v_cndmask_b32_e64 v23, v15, v203, s[68:69]
	s_branch .LBB0_889

.LBB0_889:
	v_mov_b64_e32 v[12:13], s[78:79]
	v_mad_i64_i32 v[12:13], s[28:29], v24, s26, v[12:13]
	v_cvt_pk_bf16_f32 v8, v16, v17
	v_cvt_pk_bf16_f32 v9, v18, v19
	v_cvt_pk_bf16_f32 v10, v20, v21
	v_cvt_pk_bf16_f32 v11, v22, v23
	v_lshl_add_u64 v[12:13], v[64:65], 1, v[12:13]
	s_and_b64 vcc, exec, s[38:39]
	v_add_u32_e32 v16, 0xb0, v181
	global_store_dwordx4 v[12:13], v[8:11], off offset:256 nt
	s_cbranch_vccnz .LBB0_939
	v_add_u32_e32 v182, 176, v181
	v_xor_b32_e32 v183, 16, v180
	v_and_b32_e32 v182, 0xfff, v182
	v_lshlrev_b32_e32 v183, 2, v183
	v_cvt_f32_u32_e32 v182, v182
	v_cmp_eq_u32_e64 s[60:61], 0, v171
	v_cmp_gt_u32_e64 s[68:69], 2, v171
	ds_bpermute_b32 v184, v183, v0
	ds_bpermute_b32 v185, v183, v1
	ds_bpermute_b32 v186, v183, v2
	ds_bpermute_b32 v187, v183, v3
	ds_bpermute_b32 v188, v183, v4
	ds_bpermute_b32 v189, v183, v5
	ds_bpermute_b32 v190, v183, v6
	ds_bpermute_b32 v191, v183, v7
	v_mov_b32_e32 v192, 1.0
	v_cndmask_b32_e64 v192, v192, -1.0, s[60:61]
	v_mul_f32_e32 v194, 0.15915494, v182
	v_rndne_f32_e32 v194, v194
	v_fma_f32 v194, v182, 0.15915494, -v194
	v_mul_f32_e32 v194, 0x40c90fdb, v194
	v_mul_f32_e32 v194, 0.15915494, v194
	v_sin_f32_e32 v204, v194
	v_cos_f32_e32 v196, v194
	v_mul_f32_e32 v193, 0x3e4693af, v182
	v_mul_f32_e32 v194, 0.15915494, v193
	v_rndne_f32_e32 v194, v194
	v_fma_f32 v194, v193, 0.15915494, -v194
	v_mul_f32_e32 v194, 0x40c90fdb, v194
	v_mul_f32_e32 v194, 0.15915494, v194
	v_sin_f32_e32 v205, v194
	v_cos_f32_e32 v197, v194
	v_mul_f32_e32 v193, 0x3d1a08c8, v182
	v_mul_f32_e32 v194, 0.15915494, v193
	v_rndne_f32_e32 v194, v194
	v_fma_f32 v194, v193, 0.15915494, -v194
	v_mul_f32_e32 v194, 0x40c90fdb, v194
	v_mul_f32_e32 v194, 0.15915494, v194
	v_sin_f32_e32 v206, v194
	v_cos_f32_e32 v198, v194
	v_mul_f32_e32 v193, 0x3beef74e, v182
	v_mul_f32_e32 v194, 0.15915494, v193
	v_rndne_f32_e32 v194, v194
	v_fma_f32 v194, v193, 0.15915494, -v194
	v_mul_f32_e32 v194, 0x40c90fdb, v194
	v_mul_f32_e32 v194, 0.15915494, v194
	v_sin_f32_e32 v207, v194
	v_cos_f32_e32 v199, v194
	v_mul_f32_e32 v193, 0x3ab95d22, v182
	v_mul_f32_e32 v194, 0.15915494, v193
	v_rndne_f32_e32 v194, v194
	v_fma_f32 v194, v193, 0.15915494, -v194
	v_mul_f32_e32 v194, 0x40c90fdb, v194
	v_mul_f32_e32 v194, 0.15915494, v194
	v_sin_f32_e32 v208, v194
	v_cos_f32_e32 v200, v194
	v_mul_f32_e32 v193, 0x398fc8f8, v182
	v_mul_f32_e32 v194, 0.15915494, v193
	v_rndne_f32_e32 v194, v194
	v_fma_f32 v194, v193, 0.15915494, -v194
	v_mul_f32_e32 v194, 0x40c90fdb, v194
	v_mul_f32_e32 v194, 0.15915494, v194
	v_sin_f32_e32 v209, v194
	v_cos_f32_e32 v201, v194
	v_mul_f32_e32 v193, 0x385f10c4, v182
	v_mul_f32_e32 v194, 0.15915494, v193
	v_rndne_f32_e32 v194, v194
	v_fma_f32 v194, v193, 0.15915494, -v194
	v_mul_f32_e32 v194, 0x40c90fdb, v194
	v_mul_f32_e32 v194, 0.15915494, v194
	v_sin_f32_e32 v210, v194
	v_cos_f32_e32 v202, v194
	v_mul_f32_e32 v193, 0x372d07a7, v182
	v_mul_f32_e32 v194, 0.15915494, v193
	v_rndne_f32_e32 v194, v194
	v_fma_f32 v194, v193, 0.15915494, -v194
	v_mul_f32_e32 v194, 0x40c90fdb, v194
	v_mul_f32_e32 v194, 0.15915494, v194
	v_sin_f32_e32 v211, v194
	v_cos_f32_e32 v203, v194
	s_waitcnt lgkmcnt(0)
	v_mul_f32_e32 v204, v204, v184
	v_mul_f32_e32 v196, v196, v0
	v_mul_f32_e32 v204, v204, v192
	v_add_f32_e32 v196, v196, v204
	v_cndmask_b32_e64 v8, v0, v196, s[68:69]
	v_mul_f32_e32 v205, v205, v185
	v_mul_f32_e32 v197, v197, v1
	v_mul_f32_e32 v205, v205, v192
	v_add_f32_e32 v197, v197, v205
	v_cndmask_b32_e64 v9, v1, v197, s[68:69]
	v_mul_f32_e32 v206, v206, v186
	v_mul_f32_e32 v198, v198, v2
	v_mul_f32_e32 v206, v206, v192
	v_add_f32_e32 v198, v198, v206
	v_cndmask_b32_e64 v10, v2, v198, s[68:69]
	v_mul_f32_e32 v207, v207, v187
	v_mul_f32_e32 v199, v199, v3
	v_mul_f32_e32 v207, v207, v192
	v_add_f32_e32 v199, v199, v207
	v_cndmask_b32_e64 v11, v3, v199, s[68:69]
	v_mul_f32_e32 v208, v208, v188
	v_mul_f32_e32 v200, v200, v4
	v_mul_f32_e32 v208, v208, v192
	v_add_f32_e32 v200, v200, v208
	v_cndmask_b32_e64 v12, v4, v200, s[68:69]
	v_mul_f32_e32 v209, v209, v189
	v_mul_f32_e32 v201, v201, v5
	v_mul_f32_e32 v209, v209, v192
	v_add_f32_e32 v201, v201, v209
	v_cndmask_b32_e64 v13, v5, v201, s[68:69]
	v_mul_f32_e32 v210, v210, v190
	v_mul_f32_e32 v202, v202, v6
	v_mul_f32_e32 v210, v210, v192
	v_add_f32_e32 v202, v202, v210
	v_cndmask_b32_e64 v14, v6, v202, s[68:69]
	v_mul_f32_e32 v211, v211, v191
	v_mul_f32_e32 v203, v203, v7
	v_mul_f32_e32 v211, v211, v192
	v_add_f32_e32 v203, v203, v211
	v_cndmask_b32_e64 v15, v7, v203, s[68:69]
	s_branch .LBB0_940
